# GEMM K-loops: closing s_barrier of each 32-MFMA block moved up by 4 MFMAs (handoff overlap), on top of rstd prelude fix
# baseline (speedup 1.0000x reference)
.LBB0_220:
	ds_read_b128 v[148:151], v173
	ds_read_b128 v[152:155], v173 offset:1024
	ds_read_b128 v[156:159], v173 offset:2048
	ds_read_b128 v[160:163], v173 offset:3072
	ds_read_b128 v[164:167], v174
	ds_read_b128 v[180:183], v174 offset:1024
	ds_read_b128 v[184:187], v174 offset:2048
	ds_read_b128 v[188:191], v174 offset:3072
	s_add_u32 s52, s50, 0xfffc0080
	s_addc_u32 s53, s51, -1
	s_cmp_eq_u32 s66, 12
	s_cselect_b32 s55, s9, s53
	s_cselect_b32 s54, s11, s52
	s_cselect_b32 s53, s20, s45
	s_cselect_b32 s52, s33, s43
	v_lshl_add_u64 v[168:169], s[50:51], 0, v[140:141]
	s_add_i32 m0, s35, 0xc000
	ds_read_b128 v[192:195], v175
	ds_read_b128 v[196:199], v175 offset:1024
	ds_read_b128 v[204:207], v175 offset:2048
	ds_read_b128 v[208:211], v175 offset:3072
	ds_read_b128 v[212:215], v175 offset:4096
	ds_read_b128 v[216:219], v175 offset:5120
	ds_read_b128 v[220:223], v175 offset:6144
	ds_read_b128 v[224:227], v175 offset:7168
	global_load_lds_dwordx4 v[168:169], off
	v_lshl_add_u64 v[168:169], s[50:51], 0, v[142:143]
	s_add_i32 m0, s35, 0xe000
	s_nop 0
	global_load_lds_dwordx4 v[168:169], off
	s_waitcnt vmcnt(8)
	s_waitcnt lgkmcnt(0)
	s_barrier
	s_setprio 1
	s_waitcnt lgkmcnt(0)
	v_mfma_f32_16x16x32_bf16 v[124:127], v[148:151], v[192:195], v[124:127]
	v_mfma_f32_16x16x32_bf16 v[120:123], v[156:159], v[192:195], v[120:123]
	v_mfma_f32_16x16x32_bf16 v[108:111], v[148:151], v[204:207], v[108:111]
	v_mfma_f32_16x16x32_bf16 v[104:107], v[156:159], v[204:207], v[104:107]
	v_mfma_f32_16x16x32_bf16 v[92:95], v[148:151], v[212:215], v[92:95]
	v_mfma_f32_16x16x32_bf16 v[88:91], v[156:159], v[212:215], v[88:91]
	v_mfma_f32_16x16x32_bf16 v[76:79], v[148:151], v[220:223], v[76:79]
	v_mfma_f32_16x16x32_bf16 v[72:75], v[156:159], v[220:223], v[72:75]
	v_mfma_f32_16x16x32_bf16 v[124:127], v[152:155], v[196:199], v[124:127]
	v_mfma_f32_16x16x32_bf16 v[120:123], v[160:163], v[196:199], v[120:123]
	v_mfma_f32_16x16x32_bf16 v[108:111], v[152:155], v[208:211], v[108:111]
	v_mfma_f32_16x16x32_bf16 v[104:107], v[160:163], v[208:211], v[104:107]
	v_mfma_f32_16x16x32_bf16 v[92:95], v[152:155], v[216:219], v[92:95]
	v_mfma_f32_16x16x32_bf16 v[88:91], v[160:163], v[216:219], v[88:91]
	v_mfma_f32_16x16x32_bf16 v[76:79], v[152:155], v[224:227], v[76:79]
	v_mfma_f32_16x16x32_bf16 v[72:75], v[160:163], v[224:227], v[72:75]
	s_setprio 0
	s_setprio 1
	v_mfma_f32_16x16x32_bf16 v[116:119], v[164:167], v[192:195], v[116:119]
	v_mfma_f32_16x16x32_bf16 v[112:115], v[184:187], v[192:195], v[112:115]
	v_mfma_f32_16x16x32_bf16 v[100:103], v[164:167], v[204:207], v[100:103]
	v_mfma_f32_16x16x32_bf16 v[96:99], v[184:187], v[204:207], v[96:99]
	v_mfma_f32_16x16x32_bf16 v[84:87], v[164:167], v[212:215], v[84:87]
	v_mfma_f32_16x16x32_bf16 v[80:83], v[184:187], v[212:215], v[80:83]
	v_mfma_f32_16x16x32_bf16 v[68:71], v[164:167], v[220:223], v[68:71]
	v_mfma_f32_16x16x32_bf16 v[64:67], v[184:187], v[220:223], v[64:67]
	v_mfma_f32_16x16x32_bf16 v[116:119], v[180:183], v[196:199], v[116:119]
	v_mfma_f32_16x16x32_bf16 v[112:115], v[188:191], v[196:199], v[112:115]
	v_mfma_f32_16x16x32_bf16 v[100:103], v[180:183], v[208:211], v[100:103]
	v_mfma_f32_16x16x32_bf16 v[96:99], v[188:191], v[208:211], v[96:99]
	s_barrier
	v_mfma_f32_16x16x32_bf16 v[84:87], v[180:183], v[216:219], v[84:87]
	v_mfma_f32_16x16x32_bf16 v[80:83], v[188:191], v[216:219], v[80:83]
	v_mfma_f32_16x16x32_bf16 v[68:71], v[180:183], v[224:227], v[68:71]
	v_mfma_f32_16x16x32_bf16 v[64:67], v[188:191], v[224:227], v[64:67]
	s_setprio 0
	s_add_i32 s67, s63, s31
	v_lshl_add_u64 v[168:169], s[52:53], 0, v[130:131]
	s_mov_b32 m0, s67
	ds_read_b128 v[192:195], v175 offset:16384
	ds_read_b128 v[196:199], v175 offset:17408
	ds_read_b128 v[204:207], v175 offset:18432
	ds_read_b128 v[208:211], v175 offset:19456
	ds_read_b128 v[212:215], v175 offset:20480
	ds_read_b128 v[216:219], v175 offset:21504
	ds_read_b128 v[220:223], v175 offset:22528
	ds_read_b128 v[224:227], v175 offset:23552
	global_load_lds_dwordx4 v[168:169], off
	s_add_i32 m0, s67, 0x2000
	s_add_u32 s68, s52, 0x40000
	v_lshl_add_u64 v[200:201], s[52:53], 0, v[134:135]
	s_addc_u32 s69, s53, 0
	s_add_i32 s67, s64, s31
	global_load_lds_dwordx4 v[200:201], off
	v_lshl_add_u64 v[228:229], s[68:69], 0, v[130:131]
	s_mov_b32 m0, s67
	v_lshl_add_u64 v[230:231], s[54:55], 0, v[132:133]
	global_load_lds_dwordx4 v[228:229], off
	v_lshl_add_u64 v[228:229], s[68:69], 0, v[134:135]
	s_add_i32 m0, s67, 0x2000
	s_nop 0
	global_load_lds_dwordx4 v[228:229], off
	v_lshl_add_u64 v[228:229], s[54:55], 0, v[128:129]
	s_mov_b32 m0, s35
	s_nop 0
	global_load_lds_dwordx4 v[228:229], off
	s_mov_b32 m0, s37
	s_nop 0
	global_load_lds_dwordx4 v[230:231], off
	s_waitcnt vmcnt(8)
	s_waitcnt lgkmcnt(0)
	s_barrier
	s_setprio 1
	s_waitcnt lgkmcnt(0)
	v_mfma_f32_16x16x32_bf16 v[60:63], v[148:151], v[192:195], v[60:63]
	v_mfma_f32_16x16x32_bf16 v[56:59], v[156:159], v[192:195], v[56:59]
	v_mfma_f32_16x16x32_bf16 v[44:47], v[148:151], v[204:207], v[44:47]
	v_mfma_f32_16x16x32_bf16 v[40:43], v[156:159], v[204:207], v[40:43]
	v_mfma_f32_16x16x32_bf16 v[28:31], v[148:151], v[212:215], v[28:31]
	v_mfma_f32_16x16x32_bf16 v[24:27], v[156:159], v[212:215], v[24:27]
	v_mfma_f32_16x16x32_bf16 v[12:15], v[148:151], v[220:223], v[12:15]
	v_mfma_f32_16x16x32_bf16 v[8:11], v[156:159], v[220:223], v[8:11]
	v_mfma_f32_16x16x32_bf16 v[60:63], v[152:155], v[196:199], v[60:63]
	v_mfma_f32_16x16x32_bf16 v[56:59], v[160:163], v[196:199], v[56:59]
	v_mfma_f32_16x16x32_bf16 v[44:47], v[152:155], v[208:211], v[44:47]
	v_mfma_f32_16x16x32_bf16 v[40:43], v[160:163], v[208:211], v[40:43]
	v_mfma_f32_16x16x32_bf16 v[28:31], v[152:155], v[216:219], v[28:31]
	v_mfma_f32_16x16x32_bf16 v[24:27], v[160:163], v[216:219], v[24:27]
	v_mfma_f32_16x16x32_bf16 v[12:15], v[152:155], v[224:227], v[12:15]
	v_mfma_f32_16x16x32_bf16 v[8:11], v[160:163], v[224:227], v[8:11]
	s_setprio 0
	s_setprio 1
	v_mfma_f32_16x16x32_bf16 v[52:55], v[164:167], v[192:195], v[52:55]
	v_mfma_f32_16x16x32_bf16 v[48:51], v[184:187], v[192:195], v[48:51]
	v_mfma_f32_16x16x32_bf16 v[36:39], v[164:167], v[204:207], v[36:39]
	v_mfma_f32_16x16x32_bf16 v[32:35], v[184:187], v[204:207], v[32:35]
	v_mfma_f32_16x16x32_bf16 v[20:23], v[164:167], v[212:215], v[20:23]
	v_mfma_f32_16x16x32_bf16 v[16:19], v[184:187], v[212:215], v[16:19]
	v_mfma_f32_16x16x32_bf16 v[4:7], v[164:167], v[220:223], v[4:7]
	v_mfma_f32_16x16x32_bf16 v[0:3], v[184:187], v[220:223], v[0:3]
	v_mfma_f32_16x16x32_bf16 v[52:55], v[180:183], v[196:199], v[52:55]
	v_mfma_f32_16x16x32_bf16 v[48:51], v[188:191], v[196:199], v[48:51]
	v_mfma_f32_16x16x32_bf16 v[36:39], v[180:183], v[208:211], v[36:39]
	v_mfma_f32_16x16x32_bf16 v[32:35], v[188:191], v[208:211], v[32:35]
	s_barrier
	v_mfma_f32_16x16x32_bf16 v[20:23], v[180:183], v[216:219], v[20:23]
	v_mfma_f32_16x16x32_bf16 v[16:19], v[188:191], v[216:219], v[16:19]
	v_mfma_f32_16x16x32_bf16 v[4:7], v[180:183], v[224:227], v[4:7]
	v_mfma_f32_16x16x32_bf16 v[0:3], v[188:191], v[224:227], v[0:3]
	s_setprio 0
	s_add_i32 s67, 0, 0x18000
	v_add_u32_e32 v137, s67, v171
	s_add_i32 s68, 0, 0x1c000
	ds_read_b128 v[148:151], v137
	ds_read_b128 v[152:155], v137 offset:1024
	ds_read_b128 v[156:159], v137 offset:2048
	ds_read_b128 v[160:163], v137 offset:3072
	v_add_u32_e32 v137, s68, v171
	ds_read_b128 v[164:167], v137
	ds_read_b128 v[180:183], v137 offset:1024
	ds_read_b128 v[184:187], v137 offset:2048
	ds_read_b128 v[188:191], v137 offset:3072
	s_add_u32 s54, s54, 0x40000
	s_addc_u32 s55, s55, 0
	s_mov_b32 m0, s39
	v_lshl_add_u64 v[232:233], s[54:55], 0, v[128:129]
	ds_read_b128 v[192:195], v175 offset:32768
	ds_read_b128 v[196:199], v175 offset:33792
	ds_read_b128 v[204:207], v175 offset:34816
	ds_read_b128 v[208:211], v175 offset:35840
	ds_read_b128 v[212:215], v175 offset:36864
	ds_read_b128 v[216:219], v175 offset:37888
	ds_read_b128 v[220:223], v175 offset:38912
	ds_read_b128 v[224:227], v175 offset:39936
	global_load_lds_dwordx4 v[232:233], off
	v_lshl_add_u64 v[232:233], s[54:55], 0, v[132:133]
	s_mov_b32 m0, s41
	s_nop 0
	global_load_lds_dwordx4 v[232:233], off
	s_waitcnt vmcnt(8)
	s_waitcnt lgkmcnt(0)
	s_barrier
	s_setprio 1
	s_waitcnt lgkmcnt(0)
	v_mfma_f32_16x16x32_bf16 v[124:127], v[148:151], v[192:195], v[124:127]
	v_mfma_f32_16x16x32_bf16 v[120:123], v[156:159], v[192:195], v[120:123]
	v_mfma_f32_16x16x32_bf16 v[108:111], v[148:151], v[204:207], v[108:111]
	v_mfma_f32_16x16x32_bf16 v[104:107], v[156:159], v[204:207], v[104:107]
	v_mfma_f32_16x16x32_bf16 v[92:95], v[148:151], v[212:215], v[92:95]
	v_mfma_f32_16x16x32_bf16 v[88:91], v[156:159], v[212:215], v[88:91]
	v_mfma_f32_16x16x32_bf16 v[76:79], v[148:151], v[220:223], v[76:79]
	v_mfma_f32_16x16x32_bf16 v[72:75], v[156:159], v[220:223], v[72:75]
	v_mfma_f32_16x16x32_bf16 v[124:127], v[152:155], v[196:199], v[124:127]
	v_mfma_f32_16x16x32_bf16 v[120:123], v[160:163], v[196:199], v[120:123]
	v_mfma_f32_16x16x32_bf16 v[108:111], v[152:155], v[208:211], v[108:111]
	v_mfma_f32_16x16x32_bf16 v[104:107], v[160:163], v[208:211], v[104:107]
	v_mfma_f32_16x16x32_bf16 v[92:95], v[152:155], v[216:219], v[92:95]
	v_mfma_f32_16x16x32_bf16 v[88:91], v[160:163], v[216:219], v[88:91]
	v_mfma_f32_16x16x32_bf16 v[76:79], v[152:155], v[224:227], v[76:79]
	v_mfma_f32_16x16x32_bf16 v[72:75], v[160:163], v[224:227], v[72:75]
	s_setprio 0
	s_setprio 1
	v_mfma_f32_16x16x32_bf16 v[116:119], v[164:167], v[192:195], v[116:119]
	v_mfma_f32_16x16x32_bf16 v[112:115], v[184:187], v[192:195], v[112:115]
	v_mfma_f32_16x16x32_bf16 v[100:103], v[164:167], v[204:207], v[100:103]
	v_mfma_f32_16x16x32_bf16 v[96:99], v[184:187], v[204:207], v[96:99]
	v_mfma_f32_16x16x32_bf16 v[84:87], v[164:167], v[212:215], v[84:87]
	v_mfma_f32_16x16x32_bf16 v[80:83], v[184:187], v[212:215], v[80:83]
	v_mfma_f32_16x16x32_bf16 v[68:71], v[164:167], v[220:223], v[68:71]
	v_mfma_f32_16x16x32_bf16 v[64:67], v[184:187], v[220:223], v[64:67]
	v_mfma_f32_16x16x32_bf16 v[116:119], v[180:183], v[196:199], v[116:119]
	v_mfma_f32_16x16x32_bf16 v[112:115], v[188:191], v[196:199], v[112:115]
	v_mfma_f32_16x16x32_bf16 v[100:103], v[180:183], v[208:211], v[100:103]
	v_mfma_f32_16x16x32_bf16 v[96:99], v[188:191], v[208:211], v[96:99]
	s_barrier
	v_mfma_f32_16x16x32_bf16 v[84:87], v[180:183], v[216:219], v[84:87]
	v_mfma_f32_16x16x32_bf16 v[80:83], v[188:191], v[216:219], v[80:83]
	v_mfma_f32_16x16x32_bf16 v[68:71], v[180:183], v[224:227], v[68:71]
	v_mfma_f32_16x16x32_bf16 v[64:67], v[188:191], v[224:227], v[64:67]
	s_setprio 0
	s_add_i32 s54, s67, s31
	v_lshl_add_u64 v[168:169], v[168:169], 0, s[22:23]
	s_mov_b32 m0, s54
	ds_read_b128 v[192:195], v175 offset:49152
	ds_read_b128 v[196:199], v175 offset:50176
	ds_read_b128 v[204:207], v175 offset:51200
	ds_read_b128 v[208:211], v175 offset:52224
	ds_read_b128 v[212:215], v175 offset:53248
	ds_read_b128 v[216:219], v175 offset:54272
	ds_read_b128 v[220:223], v175 offset:55296
	ds_read_b128 v[224:227], v175 offset:56320
	global_load_lds_dwordx4 v[168:169], off
	s_add_i32 m0, s54, 0x2000
	s_add_u32 s52, s52, 0x40080
	v_lshl_add_u64 v[168:169], v[200:201], 0, s[22:23]
	s_addc_u32 s53, s53, 0
	s_add_i32 s54, s68, s31
	global_load_lds_dwordx4 v[168:169], off
	v_lshl_add_u64 v[168:169], s[52:53], 0, v[130:131]
	s_mov_b32 m0, s54
	s_nop 0
	global_load_lds_dwordx4 v[168:169], off
	v_lshl_add_u64 v[168:169], s[52:53], 0, v[134:135]
	s_add_i32 m0, s54, 0x2000
	s_nop 0
	global_load_lds_dwordx4 v[168:169], off
	v_lshl_add_u64 v[168:169], v[228:229], 0, s[22:23]
	s_mov_b32 m0, s60
	s_nop 0
	global_load_lds_dwordx4 v[168:169], off
	v_lshl_add_u64 v[168:169], v[230:231], 0, s[22:23]
	s_mov_b32 m0, s61
	s_nop 0
	global_load_lds_dwordx4 v[168:169], off
	s_waitcnt vmcnt(8)
	s_waitcnt lgkmcnt(0)
	s_barrier
	s_setprio 1
	s_waitcnt lgkmcnt(0)
	v_mfma_f32_16x16x32_bf16 v[60:63], v[148:151], v[192:195], v[60:63]
	v_mfma_f32_16x16x32_bf16 v[56:59], v[156:159], v[192:195], v[56:59]
	v_mfma_f32_16x16x32_bf16 v[44:47], v[148:151], v[204:207], v[44:47]
	v_mfma_f32_16x16x32_bf16 v[40:43], v[156:159], v[204:207], v[40:43]
	v_mfma_f32_16x16x32_bf16 v[28:31], v[148:151], v[212:215], v[28:31]
	v_mfma_f32_16x16x32_bf16 v[24:27], v[156:159], v[212:215], v[24:27]
	v_mfma_f32_16x16x32_bf16 v[12:15], v[148:151], v[220:223], v[12:15]
	v_mfma_f32_16x16x32_bf16 v[8:11], v[156:159], v[220:223], v[8:11]
	v_mfma_f32_16x16x32_bf16 v[60:63], v[152:155], v[196:199], v[60:63]
	v_mfma_f32_16x16x32_bf16 v[56:59], v[160:163], v[196:199], v[56:59]
	v_mfma_f32_16x16x32_bf16 v[44:47], v[152:155], v[208:211], v[44:47]
	v_mfma_f32_16x16x32_bf16 v[40:43], v[160:163], v[208:211], v[40:43]
	v_mfma_f32_16x16x32_bf16 v[28:31], v[152:155], v[216:219], v[28:31]
	v_mfma_f32_16x16x32_bf16 v[24:27], v[160:163], v[216:219], v[24:27]
	v_mfma_f32_16x16x32_bf16 v[12:15], v[152:155], v[224:227], v[12:15]
	v_mfma_f32_16x16x32_bf16 v[8:11], v[160:163], v[224:227], v[8:11]
	s_setprio 0
	s_setprio 1
	v_mfma_f32_16x16x32_bf16 v[52:55], v[164:167], v[192:195], v[52:55]
	v_mfma_f32_16x16x32_bf16 v[48:51], v[184:187], v[192:195], v[48:51]
	v_mfma_f32_16x16x32_bf16 v[36:39], v[164:167], v[204:207], v[36:39]
	v_mfma_f32_16x16x32_bf16 v[32:35], v[184:187], v[204:207], v[32:35]
	v_mfma_f32_16x16x32_bf16 v[20:23], v[164:167], v[212:215], v[20:23]
	v_mfma_f32_16x16x32_bf16 v[16:19], v[184:187], v[212:215], v[16:19]
	v_mfma_f32_16x16x32_bf16 v[4:7], v[164:167], v[220:223], v[4:7]
	v_mfma_f32_16x16x32_bf16 v[0:3], v[184:187], v[220:223], v[0:3]
	v_mfma_f32_16x16x32_bf16 v[52:55], v[180:183], v[196:199], v[52:55]
	v_mfma_f32_16x16x32_bf16 v[48:51], v[188:191], v[196:199], v[48:51]
	v_mfma_f32_16x16x32_bf16 v[36:39], v[180:183], v[208:211], v[36:39]
	v_mfma_f32_16x16x32_bf16 v[32:35], v[188:191], v[208:211], v[32:35]
	s_barrier
	v_mfma_f32_16x16x32_bf16 v[20:23], v[180:183], v[216:219], v[20:23]
	v_mfma_f32_16x16x32_bf16 v[16:19], v[188:191], v[216:219], v[16:19]
	v_mfma_f32_16x16x32_bf16 v[4:7], v[180:183], v[224:227], v[4:7]
	v_mfma_f32_16x16x32_bf16 v[0:3], v[188:191], v[224:227], v[0:3]
	s_setprio 0
	s_add_i32 s66, s66, 2
	s_add_u32 s50, s50, 0x100
	s_addc_u32 s51, s51, 0
	s_add_u32 s43, s43, 0x100
	s_addc_u32 s45, s45, 0
	s_cmp_gt_u32 s66, 13
	s_cbranch_scc0 .LBB0_220
	s_and_b64 vcc, exec, s[24:25]
	s_cbranch_vccz .LBB0_223
	s_barrier

.LBB0_401:
	ds_read_b128 v[128:131], v189
	ds_read_b128 v[132:135], v189 offset:1024
	ds_read_b128 v[136:139], v189 offset:2048
	ds_read_b128 v[140:143], v189 offset:3072
	ds_read_b128 v[144:147], v190
	ds_read_b128 v[148:151], v190 offset:1024
	ds_read_b128 v[168:171], v190 offset:2048
	ds_read_b128 v[172:175], v190 offset:3072
	s_add_u32 s4, s42, 0xfff80080
	s_addc_u32 s5, s43, -1
	s_cmp_eq_u32 s59, 28
	s_cselect_b32 s45, s35, s5
	s_cselect_b32 s44, s41, s4
	s_cselect_b32 s5, s31, s58
	s_cselect_b32 s4, s56, s57
	v_lshl_add_u64 v[184:185], s[42:43], 0, v[160:161]
	s_add_i32 m0, s47, 0xc000
	ds_read_b128 v[176:179], v191
	ds_read_b128 v[180:183], v191 offset:1024
	ds_read_b128 v[194:197], v191 offset:2048
	ds_read_b128 v[198:201], v191 offset:3072
	ds_read_b128 v[204:207], v191 offset:4096
	ds_read_b128 v[208:211], v191 offset:5120
	ds_read_b128 v[212:215], v191 offset:6144
	ds_read_b128 v[216:219], v191 offset:7168
	global_load_lds_dwordx4 v[184:185], off
	v_lshl_add_u64 v[184:185], s[42:43], 0, v[162:163]
	s_add_i32 m0, s47, 0xe000
	s_nop 0
	global_load_lds_dwordx4 v[184:185], off
	s_waitcnt vmcnt(8)
	s_waitcnt lgkmcnt(0)
	s_barrier
	s_setprio 1
	s_waitcnt lgkmcnt(0)
	v_mfma_f32_16x16x32_bf16 v[124:127], v[128:131], v[176:179], v[124:127]
	v_mfma_f32_16x16x32_bf16 v[120:123], v[136:139], v[176:179], v[120:123]
	v_mfma_f32_16x16x32_bf16 v[108:111], v[128:131], v[194:197], v[108:111]
	v_mfma_f32_16x16x32_bf16 v[104:107], v[136:139], v[194:197], v[104:107]
	v_mfma_f32_16x16x32_bf16 v[92:95], v[128:131], v[204:207], v[92:95]
	v_mfma_f32_16x16x32_bf16 v[88:91], v[136:139], v[204:207], v[88:91]
	v_mfma_f32_16x16x32_bf16 v[76:79], v[128:131], v[212:215], v[76:79]
	v_mfma_f32_16x16x32_bf16 v[72:75], v[136:139], v[212:215], v[72:75]
	v_mfma_f32_16x16x32_bf16 v[124:127], v[132:135], v[180:183], v[124:127]
	v_mfma_f32_16x16x32_bf16 v[120:123], v[140:143], v[180:183], v[120:123]
	v_mfma_f32_16x16x32_bf16 v[108:111], v[132:135], v[198:201], v[108:111]
	v_mfma_f32_16x16x32_bf16 v[104:107], v[140:143], v[198:201], v[104:107]
	v_mfma_f32_16x16x32_bf16 v[92:95], v[132:135], v[208:211], v[92:95]
	v_mfma_f32_16x16x32_bf16 v[88:91], v[140:143], v[208:211], v[88:91]
	v_mfma_f32_16x16x32_bf16 v[76:79], v[132:135], v[216:219], v[76:79]
	v_mfma_f32_16x16x32_bf16 v[72:75], v[140:143], v[216:219], v[72:75]
	s_setprio 0
	s_setprio 1
	v_mfma_f32_16x16x32_bf16 v[116:119], v[144:147], v[176:179], v[116:119]
	v_mfma_f32_16x16x32_bf16 v[112:115], v[168:171], v[176:179], v[112:115]
	v_mfma_f32_16x16x32_bf16 v[100:103], v[144:147], v[194:197], v[100:103]
	v_mfma_f32_16x16x32_bf16 v[96:99], v[168:171], v[194:197], v[96:99]
	v_mfma_f32_16x16x32_bf16 v[84:87], v[144:147], v[204:207], v[84:87]
	v_mfma_f32_16x16x32_bf16 v[80:83], v[168:171], v[204:207], v[80:83]
	v_mfma_f32_16x16x32_bf16 v[68:71], v[144:147], v[212:215], v[68:71]
	v_mfma_f32_16x16x32_bf16 v[64:67], v[168:171], v[212:215], v[64:67]
	v_mfma_f32_16x16x32_bf16 v[116:119], v[148:151], v[180:183], v[116:119]
	v_mfma_f32_16x16x32_bf16 v[112:115], v[172:175], v[180:183], v[112:115]
	v_mfma_f32_16x16x32_bf16 v[100:103], v[148:151], v[198:201], v[100:103]
	v_mfma_f32_16x16x32_bf16 v[96:99], v[172:175], v[198:201], v[96:99]
	s_barrier
	v_mfma_f32_16x16x32_bf16 v[84:87], v[148:151], v[208:211], v[84:87]
	v_mfma_f32_16x16x32_bf16 v[80:83], v[172:175], v[208:211], v[80:83]
	v_mfma_f32_16x16x32_bf16 v[68:71], v[148:151], v[216:219], v[68:71]
	v_mfma_f32_16x16x32_bf16 v[64:67], v[172:175], v[216:219], v[64:67]
	s_setprio 0
	s_add_i32 s60, s53, s46
	v_lshl_add_u64 v[184:185], s[4:5], 0, v[154:155]
	s_mov_b32 m0, s60
	ds_read_b128 v[176:179], v191 offset:16384
	ds_read_b128 v[180:183], v191 offset:17408
	ds_read_b128 v[194:197], v191 offset:18432
	ds_read_b128 v[198:201], v191 offset:19456
	ds_read_b128 v[204:207], v191 offset:20480
	ds_read_b128 v[208:211], v191 offset:21504
	ds_read_b128 v[212:215], v191 offset:22528
	ds_read_b128 v[216:219], v191 offset:23552
	global_load_lds_dwordx4 v[184:185], off
	s_add_i32 m0, s60, 0x2000
	s_add_u32 s60, s4, 0x80000
	v_lshl_add_u64 v[220:221], s[4:5], 0, v[158:159]
	s_addc_u32 s61, s5, 0
	s_add_i32 s62, s54, s46
	global_load_lds_dwordx4 v[220:221], off
	v_lshl_add_u64 v[222:223], s[60:61], 0, v[154:155]
	s_mov_b32 m0, s62
	v_lshl_add_u64 v[224:225], s[44:45], 0, v[156:157]
	global_load_lds_dwordx4 v[222:223], off
	v_lshl_add_u64 v[222:223], s[60:61], 0, v[158:159]
	s_add_i32 m0, s62, 0x2000
	s_nop 0
	global_load_lds_dwordx4 v[222:223], off
	v_lshl_add_u64 v[222:223], s[44:45], 0, v[152:153]
	s_mov_b32 m0, s47
	s_nop 0
	global_load_lds_dwordx4 v[222:223], off
	s_mov_b32 m0, s48
	s_nop 0
	global_load_lds_dwordx4 v[224:225], off
	s_waitcnt vmcnt(8)
	s_waitcnt lgkmcnt(0)
	s_barrier
	s_setprio 1
	s_waitcnt lgkmcnt(0)
	v_mfma_f32_16x16x32_bf16 v[60:63], v[128:131], v[176:179], v[60:63]
	v_mfma_f32_16x16x32_bf16 v[56:59], v[136:139], v[176:179], v[56:59]
	v_mfma_f32_16x16x32_bf16 v[44:47], v[128:131], v[194:197], v[44:47]
	v_mfma_f32_16x16x32_bf16 v[40:43], v[136:139], v[194:197], v[40:43]
	v_mfma_f32_16x16x32_bf16 v[28:31], v[128:131], v[204:207], v[28:31]
	v_mfma_f32_16x16x32_bf16 v[24:27], v[136:139], v[204:207], v[24:27]
	v_mfma_f32_16x16x32_bf16 v[12:15], v[128:131], v[212:215], v[12:15]
	v_mfma_f32_16x16x32_bf16 v[8:11], v[136:139], v[212:215], v[8:11]
	v_mfma_f32_16x16x32_bf16 v[60:63], v[132:135], v[180:183], v[60:63]
	v_mfma_f32_16x16x32_bf16 v[56:59], v[140:143], v[180:183], v[56:59]
	v_mfma_f32_16x16x32_bf16 v[44:47], v[132:135], v[198:201], v[44:47]
	v_mfma_f32_16x16x32_bf16 v[40:43], v[140:143], v[198:201], v[40:43]
	v_mfma_f32_16x16x32_bf16 v[28:31], v[132:135], v[208:211], v[28:31]
	v_mfma_f32_16x16x32_bf16 v[24:27], v[140:143], v[208:211], v[24:27]
	v_mfma_f32_16x16x32_bf16 v[12:15], v[132:135], v[216:219], v[12:15]
	v_mfma_f32_16x16x32_bf16 v[8:11], v[140:143], v[216:219], v[8:11]
	s_setprio 0
	s_setprio 1
	v_mfma_f32_16x16x32_bf16 v[52:55], v[144:147], v[176:179], v[52:55]
	v_mfma_f32_16x16x32_bf16 v[48:51], v[168:171], v[176:179], v[48:51]
	v_mfma_f32_16x16x32_bf16 v[36:39], v[144:147], v[194:197], v[36:39]
	v_mfma_f32_16x16x32_bf16 v[32:35], v[168:171], v[194:197], v[32:35]
	v_mfma_f32_16x16x32_bf16 v[20:23], v[144:147], v[204:207], v[20:23]
	v_mfma_f32_16x16x32_bf16 v[16:19], v[168:171], v[204:207], v[16:19]
	v_mfma_f32_16x16x32_bf16 v[4:7], v[144:147], v[212:215], v[4:7]
	v_mfma_f32_16x16x32_bf16 v[0:3], v[168:171], v[212:215], v[0:3]
	v_mfma_f32_16x16x32_bf16 v[52:55], v[148:151], v[180:183], v[52:55]
	v_mfma_f32_16x16x32_bf16 v[48:51], v[172:175], v[180:183], v[48:51]
	v_mfma_f32_16x16x32_bf16 v[36:39], v[148:151], v[198:201], v[36:39]
	v_mfma_f32_16x16x32_bf16 v[32:35], v[172:175], v[198:201], v[32:35]
	s_barrier
	v_mfma_f32_16x16x32_bf16 v[20:23], v[148:151], v[208:211], v[20:23]
	v_mfma_f32_16x16x32_bf16 v[16:19], v[172:175], v[208:211], v[16:19]
	v_mfma_f32_16x16x32_bf16 v[4:7], v[148:151], v[216:219], v[4:7]
	v_mfma_f32_16x16x32_bf16 v[0:3], v[172:175], v[216:219], v[0:3]
	s_setprio 0
	s_add_i32 s60, 0, 0x18000
	s_add_i32 s61, 0, 0x1c000
	v_add_u32_e32 v140, s60, v187
	v_add_u32_e32 v172, s61, v187
	ds_read_b128 v[128:131], v140
	ds_read_b128 v[132:135], v140 offset:1024
	ds_read_b128 v[136:139], v140 offset:2048
	ds_read_b128 v[140:143], v140 offset:3072
	ds_read_b128 v[144:147], v172
	ds_read_b128 v[148:151], v172 offset:1024
	ds_read_b128 v[168:171], v172 offset:2048
	ds_read_b128 v[172:175], v172 offset:3072
	s_add_u32 s44, s44, 0x80000
	s_addc_u32 s45, s45, 0
	s_mov_b32 m0, s49
	v_lshl_add_u64 v[226:227], s[44:45], 0, v[152:153]
	ds_read_b128 v[176:179], v191 offset:32768
	ds_read_b128 v[180:183], v191 offset:33792
	ds_read_b128 v[194:197], v191 offset:34816
	ds_read_b128 v[198:201], v191 offset:35840
	ds_read_b128 v[204:207], v191 offset:36864
	ds_read_b128 v[208:211], v191 offset:37888
	ds_read_b128 v[212:215], v191 offset:38912
	ds_read_b128 v[216:219], v191 offset:39936
	global_load_lds_dwordx4 v[226:227], off
	v_lshl_add_u64 v[226:227], s[44:45], 0, v[156:157]
	s_mov_b32 m0, s50
	s_nop 0
	global_load_lds_dwordx4 v[226:227], off
	s_waitcnt vmcnt(8)
	s_waitcnt lgkmcnt(0)
	s_barrier
	s_setprio 1
	s_waitcnt lgkmcnt(0)
	v_mfma_f32_16x16x32_bf16 v[124:127], v[128:131], v[176:179], v[124:127]
	v_mfma_f32_16x16x32_bf16 v[120:123], v[136:139], v[176:179], v[120:123]
	v_mfma_f32_16x16x32_bf16 v[108:111], v[128:131], v[194:197], v[108:111]
	v_mfma_f32_16x16x32_bf16 v[104:107], v[136:139], v[194:197], v[104:107]
	v_mfma_f32_16x16x32_bf16 v[92:95], v[128:131], v[204:207], v[92:95]
	v_mfma_f32_16x16x32_bf16 v[88:91], v[136:139], v[204:207], v[88:91]
	v_mfma_f32_16x16x32_bf16 v[76:79], v[128:131], v[212:215], v[76:79]
	v_mfma_f32_16x16x32_bf16 v[72:75], v[136:139], v[212:215], v[72:75]
	v_mfma_f32_16x16x32_bf16 v[124:127], v[132:135], v[180:183], v[124:127]
	v_mfma_f32_16x16x32_bf16 v[120:123], v[140:143], v[180:183], v[120:123]
	v_mfma_f32_16x16x32_bf16 v[108:111], v[132:135], v[198:201], v[108:111]
	v_mfma_f32_16x16x32_bf16 v[104:107], v[140:143], v[198:201], v[104:107]
	v_mfma_f32_16x16x32_bf16 v[92:95], v[132:135], v[208:211], v[92:95]
	v_mfma_f32_16x16x32_bf16 v[88:91], v[140:143], v[208:211], v[88:91]
	v_mfma_f32_16x16x32_bf16 v[76:79], v[132:135], v[216:219], v[76:79]
	v_mfma_f32_16x16x32_bf16 v[72:75], v[140:143], v[216:219], v[72:75]
	s_setprio 0
	s_setprio 1
	v_mfma_f32_16x16x32_bf16 v[116:119], v[144:147], v[176:179], v[116:119]
	v_mfma_f32_16x16x32_bf16 v[112:115], v[168:171], v[176:179], v[112:115]
	v_mfma_f32_16x16x32_bf16 v[100:103], v[144:147], v[194:197], v[100:103]
	v_mfma_f32_16x16x32_bf16 v[96:99], v[168:171], v[194:197], v[96:99]
	v_mfma_f32_16x16x32_bf16 v[84:87], v[144:147], v[204:207], v[84:87]
	v_mfma_f32_16x16x32_bf16 v[80:83], v[168:171], v[204:207], v[80:83]
	v_mfma_f32_16x16x32_bf16 v[68:71], v[144:147], v[212:215], v[68:71]
	v_mfma_f32_16x16x32_bf16 v[64:67], v[168:171], v[212:215], v[64:67]
	v_mfma_f32_16x16x32_bf16 v[116:119], v[148:151], v[180:183], v[116:119]
	v_mfma_f32_16x16x32_bf16 v[112:115], v[172:175], v[180:183], v[112:115]
	v_mfma_f32_16x16x32_bf16 v[100:103], v[148:151], v[198:201], v[100:103]
	v_mfma_f32_16x16x32_bf16 v[96:99], v[172:175], v[198:201], v[96:99]
	s_barrier
	v_mfma_f32_16x16x32_bf16 v[84:87], v[148:151], v[208:211], v[84:87]
	v_mfma_f32_16x16x32_bf16 v[80:83], v[172:175], v[208:211], v[80:83]
	v_mfma_f32_16x16x32_bf16 v[68:71], v[148:151], v[216:219], v[68:71]
	v_mfma_f32_16x16x32_bf16 v[64:67], v[172:175], v[216:219], v[64:67]
	s_setprio 0
	s_add_i32 s44, s60, s46
	v_lshl_add_u64 v[184:185], v[184:185], 0, s[26:27]
	s_mov_b32 m0, s44
	ds_read_b128 v[176:179], v191 offset:49152
	ds_read_b128 v[180:183], v191 offset:50176
	ds_read_b128 v[194:197], v191 offset:51200
	ds_read_b128 v[198:201], v191 offset:52224
	ds_read_b128 v[204:207], v191 offset:53248
	ds_read_b128 v[208:211], v191 offset:54272
	ds_read_b128 v[212:215], v191 offset:55296
	ds_read_b128 v[216:219], v191 offset:56320
	global_load_lds_dwordx4 v[184:185], off
	s_add_i32 m0, s44, 0x2000
	s_add_u32 s4, s4, 0x80080
	v_lshl_add_u64 v[184:185], v[220:221], 0, s[26:27]
	s_addc_u32 s5, s5, 0
	s_add_i32 s44, s61, s46
	global_load_lds_dwordx4 v[184:185], off
	v_lshl_add_u64 v[184:185], s[4:5], 0, v[154:155]
	s_mov_b32 m0, s44
	s_nop 0
	global_load_lds_dwordx4 v[184:185], off
	v_lshl_add_u64 v[184:185], s[4:5], 0, v[158:159]
	s_add_i32 m0, s44, 0x2000
	s_nop 0
	global_load_lds_dwordx4 v[184:185], off
	v_lshl_add_u64 v[184:185], v[222:223], 0, s[26:27]
	s_mov_b32 m0, s33
	s_nop 0
	global_load_lds_dwordx4 v[184:185], off
	v_lshl_add_u64 v[184:185], v[224:225], 0, s[26:27]
	s_mov_b32 m0, s52
	s_nop 0
	global_load_lds_dwordx4 v[184:185], off
	s_waitcnt vmcnt(8)
	s_waitcnt lgkmcnt(0)
	s_barrier
	s_setprio 1
	s_waitcnt lgkmcnt(0)
	v_mfma_f32_16x16x32_bf16 v[60:63], v[128:131], v[176:179], v[60:63]
	v_mfma_f32_16x16x32_bf16 v[56:59], v[136:139], v[176:179], v[56:59]
	v_mfma_f32_16x16x32_bf16 v[44:47], v[128:131], v[194:197], v[44:47]
	v_mfma_f32_16x16x32_bf16 v[40:43], v[136:139], v[194:197], v[40:43]
	v_mfma_f32_16x16x32_bf16 v[28:31], v[128:131], v[204:207], v[28:31]
	v_mfma_f32_16x16x32_bf16 v[24:27], v[136:139], v[204:207], v[24:27]
	v_mfma_f32_16x16x32_bf16 v[12:15], v[128:131], v[212:215], v[12:15]
	v_mfma_f32_16x16x32_bf16 v[8:11], v[136:139], v[212:215], v[8:11]
	v_mfma_f32_16x16x32_bf16 v[60:63], v[132:135], v[180:183], v[60:63]
	v_mfma_f32_16x16x32_bf16 v[56:59], v[140:143], v[180:183], v[56:59]
	v_mfma_f32_16x16x32_bf16 v[44:47], v[132:135], v[198:201], v[44:47]
	v_mfma_f32_16x16x32_bf16 v[40:43], v[140:143], v[198:201], v[40:43]
	v_mfma_f32_16x16x32_bf16 v[28:31], v[132:135], v[208:211], v[28:31]
	v_mfma_f32_16x16x32_bf16 v[24:27], v[140:143], v[208:211], v[24:27]
	v_mfma_f32_16x16x32_bf16 v[12:15], v[132:135], v[216:219], v[12:15]
	v_mfma_f32_16x16x32_bf16 v[8:11], v[140:143], v[216:219], v[8:11]
	s_setprio 0
	s_setprio 1
	v_mfma_f32_16x16x32_bf16 v[52:55], v[144:147], v[176:179], v[52:55]
	v_mfma_f32_16x16x32_bf16 v[48:51], v[168:171], v[176:179], v[48:51]
	v_mfma_f32_16x16x32_bf16 v[36:39], v[144:147], v[194:197], v[36:39]
	v_mfma_f32_16x16x32_bf16 v[32:35], v[168:171], v[194:197], v[32:35]
	v_mfma_f32_16x16x32_bf16 v[20:23], v[144:147], v[204:207], v[20:23]
	v_mfma_f32_16x16x32_bf16 v[16:19], v[168:171], v[204:207], v[16:19]
	v_mfma_f32_16x16x32_bf16 v[4:7], v[144:147], v[212:215], v[4:7]
	v_mfma_f32_16x16x32_bf16 v[0:3], v[168:171], v[212:215], v[0:3]
	v_mfma_f32_16x16x32_bf16 v[52:55], v[148:151], v[180:183], v[52:55]
	v_mfma_f32_16x16x32_bf16 v[48:51], v[172:175], v[180:183], v[48:51]
	v_mfma_f32_16x16x32_bf16 v[36:39], v[148:151], v[198:201], v[36:39]
	v_mfma_f32_16x16x32_bf16 v[32:35], v[172:175], v[198:201], v[32:35]
	s_barrier
	v_mfma_f32_16x16x32_bf16 v[20:23], v[148:151], v[208:211], v[20:23]
	v_mfma_f32_16x16x32_bf16 v[16:19], v[172:175], v[208:211], v[16:19]
	v_mfma_f32_16x16x32_bf16 v[4:7], v[148:151], v[216:219], v[4:7]
	v_mfma_f32_16x16x32_bf16 v[0:3], v[172:175], v[216:219], v[0:3]
	s_setprio 0
	s_add_i32 s59, s59, 2
	s_add_u32 s42, s42, 0x100
	s_addc_u32 s43, s43, 0
	s_add_u32 s57, s57, 0x100
	s_addc_u32 s58, s58, 0
	s_cmp_gt_u32 s59, 29
	s_cbranch_scc0 .LBB0_401
	s_and_b64 vcc, exec, s[28:29]
	s_cbranch_vccz .LBB0_404
	s_barrier

.LBB0_483:
	ds_read_b128 v[146:149], v169
	ds_read_b128 v[150:153], v169 offset:1024
	ds_read_b128 v[154:157], v169 offset:2048
	ds_read_b128 v[160:163], v169 offset:3072
	ds_read_b128 v[180:183], v171
	ds_read_b128 v[184:187], v171 offset:1024
	ds_read_b128 v[188:191], v171 offset:2048
	ds_read_b128 v[192:195], v171 offset:3072
	s_add_u32 s4, s10, 0xfffc0080
	s_addc_u32 s5, s11, -1
	s_cmp_eq_u32 s56, 12
	s_cselect_b32 s13, s9, s5
	s_cselect_b32 s12, s37, s4
	s_cselect_b32 s5, s35, s55
	s_cselect_b32 s4, s53, s54
	v_lshl_add_u64 v[200:201], s[10:11], 0, v[138:139]
	s_add_i32 m0, s42, 0xc000
	ds_read_b128 v[196:199], v173
	ds_read_b128 v[204:207], v173 offset:1024
	ds_read_b128 v[208:211], v173 offset:2048
	ds_read_b128 v[212:215], v173 offset:3072
	ds_read_b128 v[216:219], v173 offset:4096
	ds_read_b128 v[220:223], v173 offset:5120
	ds_read_b128 v[224:227], v173 offset:6144
	ds_read_b128 v[228:231], v173 offset:7168
	global_load_lds_dwordx4 v[200:201], off
	v_lshl_add_u64 v[200:201], s[10:11], 0, v[140:141]
	s_add_i32 m0, s42, 0xe000
	s_nop 0
	global_load_lds_dwordx4 v[200:201], off
	s_waitcnt vmcnt(8)
	s_waitcnt lgkmcnt(0)
	s_barrier
	s_setprio 1
	s_waitcnt lgkmcnt(0)
	v_mfma_f32_16x16x32_bf16 v[124:127], v[146:149], v[196:199], v[124:127]
	v_mfma_f32_16x16x32_bf16 v[116:119], v[154:157], v[196:199], v[116:119]
	v_mfma_f32_16x16x32_bf16 v[108:111], v[146:149], v[208:211], v[108:111]
	v_mfma_f32_16x16x32_bf16 v[100:103], v[154:157], v[208:211], v[100:103]
	v_mfma_f32_16x16x32_bf16 v[92:95], v[146:149], v[216:219], v[92:95]
	v_mfma_f32_16x16x32_bf16 v[84:87], v[154:157], v[216:219], v[84:87]
	v_mfma_f32_16x16x32_bf16 v[76:79], v[146:149], v[224:227], v[76:79]
	v_mfma_f32_16x16x32_bf16 v[68:71], v[154:157], v[224:227], v[68:71]
	v_mfma_f32_16x16x32_bf16 v[124:127], v[150:153], v[204:207], v[124:127]
	v_mfma_f32_16x16x32_bf16 v[116:119], v[160:163], v[204:207], v[116:119]
	v_mfma_f32_16x16x32_bf16 v[108:111], v[150:153], v[212:215], v[108:111]
	v_mfma_f32_16x16x32_bf16 v[100:103], v[160:163], v[212:215], v[100:103]
	v_mfma_f32_16x16x32_bf16 v[92:95], v[150:153], v[220:223], v[92:95]
	v_mfma_f32_16x16x32_bf16 v[84:87], v[160:163], v[220:223], v[84:87]
	v_mfma_f32_16x16x32_bf16 v[76:79], v[150:153], v[228:231], v[76:79]
	v_mfma_f32_16x16x32_bf16 v[68:71], v[160:163], v[228:231], v[68:71]
	s_setprio 0
	s_setprio 1
	v_mfma_f32_16x16x32_bf16 v[120:123], v[180:183], v[196:199], v[120:123]
	v_mfma_f32_16x16x32_bf16 v[112:115], v[188:191], v[196:199], v[112:115]
	v_mfma_f32_16x16x32_bf16 v[104:107], v[180:183], v[208:211], v[104:107]
	v_mfma_f32_16x16x32_bf16 v[96:99], v[188:191], v[208:211], v[96:99]
	v_mfma_f32_16x16x32_bf16 v[88:91], v[180:183], v[216:219], v[88:91]
	v_mfma_f32_16x16x32_bf16 v[80:83], v[188:191], v[216:219], v[80:83]
	v_mfma_f32_16x16x32_bf16 v[72:75], v[180:183], v[224:227], v[72:75]
	v_mfma_f32_16x16x32_bf16 v[64:67], v[188:191], v[224:227], v[64:67]
	v_mfma_f32_16x16x32_bf16 v[120:123], v[184:187], v[204:207], v[120:123]
	v_mfma_f32_16x16x32_bf16 v[112:115], v[192:195], v[204:207], v[112:115]
	v_mfma_f32_16x16x32_bf16 v[104:107], v[184:187], v[212:215], v[104:107]
	v_mfma_f32_16x16x32_bf16 v[96:99], v[192:195], v[212:215], v[96:99]
	s_barrier
	v_mfma_f32_16x16x32_bf16 v[88:91], v[184:187], v[220:223], v[88:91]
	v_mfma_f32_16x16x32_bf16 v[80:83], v[192:195], v[220:223], v[80:83]
	v_mfma_f32_16x16x32_bf16 v[72:75], v[184:187], v[228:231], v[72:75]
	v_mfma_f32_16x16x32_bf16 v[64:67], v[192:195], v[228:231], v[64:67]
	s_setprio 0
	s_add_i32 s57, s49, s23
	v_lshl_add_u64 v[200:201], s[4:5], 0, v[132:133]
	s_mov_b32 m0, s57
	ds_read_b128 v[196:199], v173 offset:16384
	ds_read_b128 v[204:207], v173 offset:17408
	ds_read_b128 v[208:211], v173 offset:18432
	ds_read_b128 v[212:215], v173 offset:19456
	ds_read_b128 v[216:219], v173 offset:20480
	ds_read_b128 v[220:223], v173 offset:21504
	ds_read_b128 v[224:227], v173 offset:22528
	ds_read_b128 v[228:231], v173 offset:23552
	global_load_lds_dwordx4 v[200:201], off
	s_add_i32 m0, s57, 0x2000
	s_add_u32 s58, s4, 0x40000
	v_lshl_add_u64 v[232:233], s[4:5], 0, v[128:129]
	s_addc_u32 s59, s5, 0
	s_add_i32 s57, s50, s23
	global_load_lds_dwordx4 v[232:233], off
	v_lshl_add_u64 v[234:235], s[58:59], 0, v[132:133]
	s_mov_b32 m0, s57
	v_lshl_add_u64 v[236:237], s[12:13], 0, v[130:131]
	global_load_lds_dwordx4 v[234:235], off
	v_lshl_add_u64 v[234:235], s[58:59], 0, v[128:129]
	s_add_i32 m0, s57, 0x2000
	s_nop 0
	global_load_lds_dwordx4 v[234:235], off
	v_lshl_add_u64 v[234:235], s[12:13], 0, v[134:135]
	s_mov_b32 m0, s42
	s_nop 0
	global_load_lds_dwordx4 v[234:235], off
	s_mov_b32 m0, s43
	s_nop 0
	global_load_lds_dwordx4 v[236:237], off
	s_waitcnt vmcnt(8)
	s_waitcnt lgkmcnt(0)
	s_barrier
	s_setprio 1
	s_waitcnt lgkmcnt(0)
	v_mfma_f32_16x16x32_bf16 v[60:63], v[146:149], v[196:199], v[60:63]
	v_mfma_f32_16x16x32_bf16 v[52:55], v[154:157], v[196:199], v[52:55]
	v_mfma_f32_16x16x32_bf16 v[44:47], v[146:149], v[208:211], v[44:47]
	v_mfma_f32_16x16x32_bf16 v[36:39], v[154:157], v[208:211], v[36:39]
	v_mfma_f32_16x16x32_bf16 v[28:31], v[146:149], v[216:219], v[28:31]
	v_mfma_f32_16x16x32_bf16 v[20:23], v[154:157], v[216:219], v[20:23]
	v_mfma_f32_16x16x32_bf16 v[12:15], v[146:149], v[224:227], v[12:15]
	v_mfma_f32_16x16x32_bf16 v[4:7], v[154:157], v[224:227], v[4:7]
	v_mfma_f32_16x16x32_bf16 v[60:63], v[150:153], v[204:207], v[60:63]
	v_mfma_f32_16x16x32_bf16 v[52:55], v[160:163], v[204:207], v[52:55]
	v_mfma_f32_16x16x32_bf16 v[44:47], v[150:153], v[212:215], v[44:47]
	v_mfma_f32_16x16x32_bf16 v[36:39], v[160:163], v[212:215], v[36:39]
	v_mfma_f32_16x16x32_bf16 v[28:31], v[150:153], v[220:223], v[28:31]
	v_mfma_f32_16x16x32_bf16 v[20:23], v[160:163], v[220:223], v[20:23]
	v_mfma_f32_16x16x32_bf16 v[12:15], v[150:153], v[228:231], v[12:15]
	v_mfma_f32_16x16x32_bf16 v[4:7], v[160:163], v[228:231], v[4:7]
	s_setprio 0
	s_setprio 1
	v_mfma_f32_16x16x32_bf16 v[56:59], v[180:183], v[196:199], v[56:59]
	v_mfma_f32_16x16x32_bf16 v[48:51], v[188:191], v[196:199], v[48:51]
	v_mfma_f32_16x16x32_bf16 v[40:43], v[180:183], v[208:211], v[40:43]
	v_mfma_f32_16x16x32_bf16 v[32:35], v[188:191], v[208:211], v[32:35]
	v_mfma_f32_16x16x32_bf16 v[24:27], v[180:183], v[216:219], v[24:27]
	v_mfma_f32_16x16x32_bf16 v[16:19], v[188:191], v[216:219], v[16:19]
	v_mfma_f32_16x16x32_bf16 v[8:11], v[180:183], v[224:227], v[8:11]
	v_mfma_f32_16x16x32_bf16 v[0:3], v[188:191], v[224:227], v[0:3]
	v_mfma_f32_16x16x32_bf16 v[56:59], v[184:187], v[204:207], v[56:59]
	v_mfma_f32_16x16x32_bf16 v[48:51], v[192:195], v[204:207], v[48:51]
	v_mfma_f32_16x16x32_bf16 v[40:43], v[184:187], v[212:215], v[40:43]
	v_mfma_f32_16x16x32_bf16 v[32:35], v[192:195], v[212:215], v[32:35]
	s_barrier
	v_mfma_f32_16x16x32_bf16 v[24:27], v[184:187], v[220:223], v[24:27]
	v_mfma_f32_16x16x32_bf16 v[16:19], v[192:195], v[220:223], v[16:19]
	v_mfma_f32_16x16x32_bf16 v[8:11], v[184:187], v[228:231], v[8:11]
	v_mfma_f32_16x16x32_bf16 v[0:3], v[192:195], v[228:231], v[0:3]
	s_setprio 0
	s_add_i32 s57, 0, 0x18000
	v_add_u32_e32 v158, s57, v165
	s_add_i32 s58, 0, 0x1c000
	ds_read_b128 v[146:149], v158
	ds_read_b128 v[150:153], v158 offset:1024
	ds_read_b128 v[154:157], v158 offset:2048
	ds_read_b128 v[160:163], v158 offset:3072
	v_add_u32_e32 v158, s58, v165
	ds_read_b128 v[180:183], v158
	ds_read_b128 v[184:187], v158 offset:1024
	ds_read_b128 v[188:191], v158 offset:2048
	ds_read_b128 v[192:195], v158 offset:3072
	s_add_u32 s12, s12, 0x40000
	s_addc_u32 s13, s13, 0
	s_mov_b32 m0, s44
	v_lshl_add_u64 v[238:239], s[12:13], 0, v[134:135]
	ds_read_b128 v[196:199], v173 offset:32768
	ds_read_b128 v[204:207], v173 offset:33792
	ds_read_b128 v[208:211], v173 offset:34816
	ds_read_b128 v[212:215], v173 offset:35840
	ds_read_b128 v[216:219], v173 offset:36864
	ds_read_b128 v[220:223], v173 offset:37888
	ds_read_b128 v[224:227], v173 offset:38912
	ds_read_b128 v[228:231], v173 offset:39936
	global_load_lds_dwordx4 v[238:239], off
	v_lshl_add_u64 v[238:239], s[12:13], 0, v[130:131]
	s_mov_b32 m0, s45
	s_nop 0
	global_load_lds_dwordx4 v[238:239], off
	s_waitcnt vmcnt(8)
	s_waitcnt lgkmcnt(0)
	s_barrier
	s_setprio 1
	s_waitcnt lgkmcnt(0)
	v_mfma_f32_16x16x32_bf16 v[124:127], v[146:149], v[196:199], v[124:127]
	v_mfma_f32_16x16x32_bf16 v[116:119], v[154:157], v[196:199], v[116:119]
	v_mfma_f32_16x16x32_bf16 v[108:111], v[146:149], v[208:211], v[108:111]
	v_mfma_f32_16x16x32_bf16 v[100:103], v[154:157], v[208:211], v[100:103]
	v_mfma_f32_16x16x32_bf16 v[92:95], v[146:149], v[216:219], v[92:95]
	v_mfma_f32_16x16x32_bf16 v[84:87], v[154:157], v[216:219], v[84:87]
	v_mfma_f32_16x16x32_bf16 v[76:79], v[146:149], v[224:227], v[76:79]
	v_mfma_f32_16x16x32_bf16 v[68:71], v[154:157], v[224:227], v[68:71]
	v_mfma_f32_16x16x32_bf16 v[124:127], v[150:153], v[204:207], v[124:127]
	v_mfma_f32_16x16x32_bf16 v[116:119], v[160:163], v[204:207], v[116:119]
	v_mfma_f32_16x16x32_bf16 v[108:111], v[150:153], v[212:215], v[108:111]
	v_mfma_f32_16x16x32_bf16 v[100:103], v[160:163], v[212:215], v[100:103]
	v_mfma_f32_16x16x32_bf16 v[92:95], v[150:153], v[220:223], v[92:95]
	v_mfma_f32_16x16x32_bf16 v[84:87], v[160:163], v[220:223], v[84:87]
	v_mfma_f32_16x16x32_bf16 v[76:79], v[150:153], v[228:231], v[76:79]
	v_mfma_f32_16x16x32_bf16 v[68:71], v[160:163], v[228:231], v[68:71]
	s_setprio 0
	s_setprio 1
	v_mfma_f32_16x16x32_bf16 v[120:123], v[180:183], v[196:199], v[120:123]
	v_mfma_f32_16x16x32_bf16 v[112:115], v[188:191], v[196:199], v[112:115]
	v_mfma_f32_16x16x32_bf16 v[104:107], v[180:183], v[208:211], v[104:107]
	v_mfma_f32_16x16x32_bf16 v[96:99], v[188:191], v[208:211], v[96:99]
	v_mfma_f32_16x16x32_bf16 v[88:91], v[180:183], v[216:219], v[88:91]
	v_mfma_f32_16x16x32_bf16 v[80:83], v[188:191], v[216:219], v[80:83]
	v_mfma_f32_16x16x32_bf16 v[72:75], v[180:183], v[224:227], v[72:75]
	v_mfma_f32_16x16x32_bf16 v[64:67], v[188:191], v[224:227], v[64:67]
	v_mfma_f32_16x16x32_bf16 v[120:123], v[184:187], v[204:207], v[120:123]
	v_mfma_f32_16x16x32_bf16 v[112:115], v[192:195], v[204:207], v[112:115]
	v_mfma_f32_16x16x32_bf16 v[104:107], v[184:187], v[212:215], v[104:107]
	v_mfma_f32_16x16x32_bf16 v[96:99], v[192:195], v[212:215], v[96:99]
	s_barrier
	v_mfma_f32_16x16x32_bf16 v[88:91], v[184:187], v[220:223], v[88:91]
	v_mfma_f32_16x16x32_bf16 v[80:83], v[192:195], v[220:223], v[80:83]
	v_mfma_f32_16x16x32_bf16 v[72:75], v[184:187], v[228:231], v[72:75]
	v_mfma_f32_16x16x32_bf16 v[64:67], v[192:195], v[228:231], v[64:67]
	s_setprio 0
	s_add_i32 s12, s57, s23
	v_lshl_add_u64 v[200:201], v[200:201], 0, s[28:29]
	s_mov_b32 m0, s12
	ds_read_b128 v[196:199], v173 offset:49152
	ds_read_b128 v[204:207], v173 offset:50176
	ds_read_b128 v[208:211], v173 offset:51200
	ds_read_b128 v[212:215], v173 offset:52224
	ds_read_b128 v[216:219], v173 offset:53248
	ds_read_b128 v[220:223], v173 offset:54272
	ds_read_b128 v[224:227], v173 offset:55296
	ds_read_b128 v[228:231], v173 offset:56320
	global_load_lds_dwordx4 v[200:201], off
	s_add_i32 m0, s12, 0x2000
	s_add_u32 s4, s4, 0x40080
	v_lshl_add_u64 v[200:201], v[232:233], 0, s[28:29]
	s_addc_u32 s5, s5, 0
	s_add_i32 s12, s58, s23
	global_load_lds_dwordx4 v[200:201], off
	v_lshl_add_u64 v[200:201], s[4:5], 0, v[132:133]
	s_mov_b32 m0, s12
	s_nop 0
	global_load_lds_dwordx4 v[200:201], off
	v_lshl_add_u64 v[200:201], s[4:5], 0, v[128:129]
	s_add_i32 m0, s12, 0x2000
	s_nop 0
	global_load_lds_dwordx4 v[200:201], off
	v_lshl_add_u64 v[200:201], v[234:235], 0, s[28:29]
	s_mov_b32 m0, s47
	s_nop 0
	global_load_lds_dwordx4 v[200:201], off
	v_lshl_add_u64 v[200:201], v[236:237], 0, s[28:29]
	s_mov_b32 m0, s48
	s_nop 0
	global_load_lds_dwordx4 v[200:201], off
	s_waitcnt vmcnt(8)
	s_waitcnt lgkmcnt(0)
	s_barrier
	s_setprio 1
	s_waitcnt lgkmcnt(0)
	v_mfma_f32_16x16x32_bf16 v[60:63], v[146:149], v[196:199], v[60:63]
	v_mfma_f32_16x16x32_bf16 v[52:55], v[154:157], v[196:199], v[52:55]
	v_mfma_f32_16x16x32_bf16 v[44:47], v[146:149], v[208:211], v[44:47]
	v_mfma_f32_16x16x32_bf16 v[36:39], v[154:157], v[208:211], v[36:39]
	v_mfma_f32_16x16x32_bf16 v[28:31], v[146:149], v[216:219], v[28:31]
	v_mfma_f32_16x16x32_bf16 v[20:23], v[154:157], v[216:219], v[20:23]
	v_mfma_f32_16x16x32_bf16 v[12:15], v[146:149], v[224:227], v[12:15]
	v_mfma_f32_16x16x32_bf16 v[4:7], v[154:157], v[224:227], v[4:7]
	v_mfma_f32_16x16x32_bf16 v[60:63], v[150:153], v[204:207], v[60:63]
	v_mfma_f32_16x16x32_bf16 v[52:55], v[160:163], v[204:207], v[52:55]
	v_mfma_f32_16x16x32_bf16 v[44:47], v[150:153], v[212:215], v[44:47]
	v_mfma_f32_16x16x32_bf16 v[36:39], v[160:163], v[212:215], v[36:39]
	v_mfma_f32_16x16x32_bf16 v[28:31], v[150:153], v[220:223], v[28:31]
	v_mfma_f32_16x16x32_bf16 v[20:23], v[160:163], v[220:223], v[20:23]
	v_mfma_f32_16x16x32_bf16 v[12:15], v[150:153], v[228:231], v[12:15]
	v_mfma_f32_16x16x32_bf16 v[4:7], v[160:163], v[228:231], v[4:7]
	s_setprio 0
	s_setprio 1
	v_mfma_f32_16x16x32_bf16 v[56:59], v[180:183], v[196:199], v[56:59]
	v_mfma_f32_16x16x32_bf16 v[48:51], v[188:191], v[196:199], v[48:51]
	v_mfma_f32_16x16x32_bf16 v[40:43], v[180:183], v[208:211], v[40:43]
	v_mfma_f32_16x16x32_bf16 v[32:35], v[188:191], v[208:211], v[32:35]
	v_mfma_f32_16x16x32_bf16 v[24:27], v[180:183], v[216:219], v[24:27]
	v_mfma_f32_16x16x32_bf16 v[16:19], v[188:191], v[216:219], v[16:19]
	v_mfma_f32_16x16x32_bf16 v[8:11], v[180:183], v[224:227], v[8:11]
	v_mfma_f32_16x16x32_bf16 v[0:3], v[188:191], v[224:227], v[0:3]
	v_mfma_f32_16x16x32_bf16 v[56:59], v[184:187], v[204:207], v[56:59]
	v_mfma_f32_16x16x32_bf16 v[48:51], v[192:195], v[204:207], v[48:51]
	v_mfma_f32_16x16x32_bf16 v[40:43], v[184:187], v[212:215], v[40:43]
	v_mfma_f32_16x16x32_bf16 v[32:35], v[192:195], v[212:215], v[32:35]
	s_barrier
	v_mfma_f32_16x16x32_bf16 v[24:27], v[184:187], v[220:223], v[24:27]
	v_mfma_f32_16x16x32_bf16 v[16:19], v[192:195], v[220:223], v[16:19]
	v_mfma_f32_16x16x32_bf16 v[8:11], v[184:187], v[228:231], v[8:11]
	v_mfma_f32_16x16x32_bf16 v[0:3], v[192:195], v[228:231], v[0:3]
	s_setprio 0
	s_add_i32 s56, s56, 2
	s_add_u32 s10, s10, 0x100
	s_addc_u32 s11, s11, 0
	s_add_u32 s54, s54, 0x100
	s_addc_u32 s55, s55, 0
	s_cmp_gt_u32 s56, 13
	s_cbranch_scc0 .LBB0_483
	s_and_b64 vcc, exec, s[30:31]
	s_cbranch_vccz .LBB0_486
	s_barrier

.LBB0_559:
	ds_read_b128 v[128:131], v189
	ds_read_b128 v[132:135], v189 offset:1024
	ds_read_b128 v[136:139], v189 offset:2048
	ds_read_b128 v[140:143], v189 offset:3072
	ds_read_b128 v[144:147], v190
	ds_read_b128 v[148:151], v190 offset:1024
	ds_read_b128 v[168:171], v190 offset:2048
	ds_read_b128 v[172:175], v190 offset:3072
	s_add_u32 s4, s22, 0x100
	s_addc_u32 s5, s23, 0
	s_cmp_eq_u32 s57, 40
	s_cselect_b32 s41, s11, s5
	s_cselect_b32 s40, s10, s4
	s_cselect_b32 s39, s37, s56
	s_cselect_b32 s38, s36, s55
	v_lshl_add_u64 v[184:185], s[22:23], 0, v[160:161]
	s_add_i32 m0, s43, 0xc000
	ds_read_b128 v[176:179], v191
	ds_read_b128 v[180:183], v191 offset:1024
	ds_read_b128 v[194:197], v191 offset:2048
	ds_read_b128 v[198:201], v191 offset:3072
	ds_read_b128 v[204:207], v191 offset:4096
	ds_read_b128 v[208:211], v191 offset:5120
	ds_read_b128 v[212:215], v191 offset:6144
	ds_read_b128 v[216:219], v191 offset:7168
	global_load_lds_dwordx4 v[184:185], off
	v_lshl_add_u64 v[184:185], s[22:23], 0, v[162:163]
	s_add_i32 m0, s43, 0xe000
	s_nop 0
	global_load_lds_dwordx4 v[184:185], off
	s_waitcnt vmcnt(8)
	s_waitcnt lgkmcnt(0)
	s_barrier
	s_setprio 1
	s_waitcnt lgkmcnt(0)
	v_mfma_f32_16x16x32_bf16 v[124:127], v[128:131], v[176:179], v[124:127]
	v_mfma_f32_16x16x32_bf16 v[120:123], v[136:139], v[176:179], v[120:123]
	v_mfma_f32_16x16x32_bf16 v[108:111], v[128:131], v[194:197], v[108:111]
	v_mfma_f32_16x16x32_bf16 v[104:107], v[136:139], v[194:197], v[104:107]
	v_mfma_f32_16x16x32_bf16 v[92:95], v[128:131], v[204:207], v[92:95]
	v_mfma_f32_16x16x32_bf16 v[88:91], v[136:139], v[204:207], v[88:91]
	v_mfma_f32_16x16x32_bf16 v[76:79], v[128:131], v[212:215], v[76:79]
	v_mfma_f32_16x16x32_bf16 v[72:75], v[136:139], v[212:215], v[72:75]
	v_mfma_f32_16x16x32_bf16 v[124:127], v[132:135], v[180:183], v[124:127]
	v_mfma_f32_16x16x32_bf16 v[120:123], v[140:143], v[180:183], v[120:123]
	v_mfma_f32_16x16x32_bf16 v[108:111], v[132:135], v[198:201], v[108:111]
	v_mfma_f32_16x16x32_bf16 v[104:107], v[140:143], v[198:201], v[104:107]
	v_mfma_f32_16x16x32_bf16 v[92:95], v[132:135], v[208:211], v[92:95]
	v_mfma_f32_16x16x32_bf16 v[88:91], v[140:143], v[208:211], v[88:91]
	v_mfma_f32_16x16x32_bf16 v[76:79], v[132:135], v[216:219], v[76:79]
	v_mfma_f32_16x16x32_bf16 v[72:75], v[140:143], v[216:219], v[72:75]
	s_setprio 0
	s_setprio 1
	v_mfma_f32_16x16x32_bf16 v[116:119], v[144:147], v[176:179], v[116:119]
	v_mfma_f32_16x16x32_bf16 v[112:115], v[168:171], v[176:179], v[112:115]
	v_mfma_f32_16x16x32_bf16 v[100:103], v[144:147], v[194:197], v[100:103]
	v_mfma_f32_16x16x32_bf16 v[96:99], v[168:171], v[194:197], v[96:99]
	v_mfma_f32_16x16x32_bf16 v[84:87], v[144:147], v[204:207], v[84:87]
	v_mfma_f32_16x16x32_bf16 v[80:83], v[168:171], v[204:207], v[80:83]
	v_mfma_f32_16x16x32_bf16 v[68:71], v[144:147], v[212:215], v[68:71]
	v_mfma_f32_16x16x32_bf16 v[64:67], v[168:171], v[212:215], v[64:67]
	v_mfma_f32_16x16x32_bf16 v[116:119], v[148:151], v[180:183], v[116:119]
	v_mfma_f32_16x16x32_bf16 v[112:115], v[172:175], v[180:183], v[112:115]
	v_mfma_f32_16x16x32_bf16 v[100:103], v[148:151], v[198:201], v[100:103]
	v_mfma_f32_16x16x32_bf16 v[96:99], v[172:175], v[198:201], v[96:99]
	s_barrier
	v_mfma_f32_16x16x32_bf16 v[84:87], v[148:151], v[208:211], v[84:87]
	v_mfma_f32_16x16x32_bf16 v[80:83], v[172:175], v[208:211], v[80:83]
	v_mfma_f32_16x16x32_bf16 v[68:71], v[148:151], v[216:219], v[68:71]
	v_mfma_f32_16x16x32_bf16 v[64:67], v[172:175], v[216:219], v[64:67]
	s_setprio 0
	s_add_i32 s22, s49, s42
	v_lshl_add_u64 v[184:185], s[38:39], 0, v[154:155]
	s_mov_b32 m0, s22
	ds_read_b128 v[176:179], v191 offset:16384
	ds_read_b128 v[180:183], v191 offset:17408
	ds_read_b128 v[194:197], v191 offset:18432
	ds_read_b128 v[198:201], v191 offset:19456
	ds_read_b128 v[204:207], v191 offset:20480
	ds_read_b128 v[208:211], v191 offset:21504
	ds_read_b128 v[212:215], v191 offset:22528
	ds_read_b128 v[216:219], v191 offset:23552
	global_load_lds_dwordx4 v[184:185], off
	s_add_i32 m0, s22, 0x2000
	s_add_u32 s22, s38, 0xb0000
	v_lshl_add_u64 v[220:221], s[38:39], 0, v[158:159]
	s_addc_u32 s23, s39, 0
	s_add_i32 s58, s50, s42
	global_load_lds_dwordx4 v[220:221], off
	v_lshl_add_u64 v[222:223], s[22:23], 0, v[154:155]
	s_mov_b32 m0, s58
	v_lshl_add_u64 v[224:225], s[40:41], 0, v[156:157]
	global_load_lds_dwordx4 v[222:223], off
	v_lshl_add_u64 v[222:223], s[22:23], 0, v[158:159]
	s_add_i32 m0, s58, 0x2000
	s_nop 0
	global_load_lds_dwordx4 v[222:223], off
	v_lshl_add_u64 v[222:223], s[40:41], 0, v[152:153]
	s_mov_b32 m0, s43
	s_nop 0
	global_load_lds_dwordx4 v[222:223], off
	s_mov_b32 m0, s44
	s_nop 0
	global_load_lds_dwordx4 v[224:225], off
	s_waitcnt vmcnt(8)
	s_waitcnt lgkmcnt(0)
	s_barrier
	s_setprio 1
	s_waitcnt lgkmcnt(0)
	v_mfma_f32_16x16x32_bf16 v[60:63], v[128:131], v[176:179], v[60:63]
	v_mfma_f32_16x16x32_bf16 v[56:59], v[136:139], v[176:179], v[56:59]
	v_mfma_f32_16x16x32_bf16 v[44:47], v[128:131], v[194:197], v[44:47]
	v_mfma_f32_16x16x32_bf16 v[40:43], v[136:139], v[194:197], v[40:43]
	v_mfma_f32_16x16x32_bf16 v[28:31], v[128:131], v[204:207], v[28:31]
	v_mfma_f32_16x16x32_bf16 v[24:27], v[136:139], v[204:207], v[24:27]
	v_mfma_f32_16x16x32_bf16 v[12:15], v[128:131], v[212:215], v[12:15]
	v_mfma_f32_16x16x32_bf16 v[8:11], v[136:139], v[212:215], v[8:11]
	v_mfma_f32_16x16x32_bf16 v[60:63], v[132:135], v[180:183], v[60:63]
	v_mfma_f32_16x16x32_bf16 v[56:59], v[140:143], v[180:183], v[56:59]
	v_mfma_f32_16x16x32_bf16 v[44:47], v[132:135], v[198:201], v[44:47]
	v_mfma_f32_16x16x32_bf16 v[40:43], v[140:143], v[198:201], v[40:43]
	v_mfma_f32_16x16x32_bf16 v[28:31], v[132:135], v[208:211], v[28:31]
	v_mfma_f32_16x16x32_bf16 v[24:27], v[140:143], v[208:211], v[24:27]
	v_mfma_f32_16x16x32_bf16 v[12:15], v[132:135], v[216:219], v[12:15]
	v_mfma_f32_16x16x32_bf16 v[8:11], v[140:143], v[216:219], v[8:11]
	s_setprio 0
	s_setprio 1
	v_mfma_f32_16x16x32_bf16 v[52:55], v[144:147], v[176:179], v[52:55]
	v_mfma_f32_16x16x32_bf16 v[48:51], v[168:171], v[176:179], v[48:51]
	v_mfma_f32_16x16x32_bf16 v[36:39], v[144:147], v[194:197], v[36:39]
	v_mfma_f32_16x16x32_bf16 v[32:35], v[168:171], v[194:197], v[32:35]
	v_mfma_f32_16x16x32_bf16 v[20:23], v[144:147], v[204:207], v[20:23]
	v_mfma_f32_16x16x32_bf16 v[16:19], v[168:171], v[204:207], v[16:19]
	v_mfma_f32_16x16x32_bf16 v[4:7], v[144:147], v[212:215], v[4:7]
	v_mfma_f32_16x16x32_bf16 v[0:3], v[168:171], v[212:215], v[0:3]
	v_mfma_f32_16x16x32_bf16 v[52:55], v[148:151], v[180:183], v[52:55]
	v_mfma_f32_16x16x32_bf16 v[48:51], v[172:175], v[180:183], v[48:51]
	v_mfma_f32_16x16x32_bf16 v[36:39], v[148:151], v[198:201], v[36:39]
	v_mfma_f32_16x16x32_bf16 v[32:35], v[172:175], v[198:201], v[32:35]
	s_barrier
	v_mfma_f32_16x16x32_bf16 v[20:23], v[148:151], v[208:211], v[20:23]
	v_mfma_f32_16x16x32_bf16 v[16:19], v[172:175], v[208:211], v[16:19]
	v_mfma_f32_16x16x32_bf16 v[4:7], v[148:151], v[216:219], v[4:7]
	v_mfma_f32_16x16x32_bf16 v[0:3], v[172:175], v[216:219], v[0:3]
	s_setprio 0
	s_add_i32 s58, 0, 0x18000
	s_add_i32 s59, 0, 0x1c000
	v_add_u32_e32 v140, s58, v187
	v_add_u32_e32 v172, s59, v187
	ds_read_b128 v[128:131], v140
	ds_read_b128 v[132:135], v140 offset:1024
	ds_read_b128 v[136:139], v140 offset:2048
	ds_read_b128 v[140:143], v140 offset:3072
	ds_read_b128 v[144:147], v172
	ds_read_b128 v[148:151], v172 offset:1024
	ds_read_b128 v[168:171], v172 offset:2048
	ds_read_b128 v[172:175], v172 offset:3072
	s_add_u32 s22, s40, 0xb0000
	s_addc_u32 s23, s41, 0
	s_mov_b32 m0, s45
	v_lshl_add_u64 v[226:227], s[22:23], 0, v[152:153]
	ds_read_b128 v[176:179], v191 offset:32768
	ds_read_b128 v[180:183], v191 offset:33792
	ds_read_b128 v[194:197], v191 offset:34816
	ds_read_b128 v[198:201], v191 offset:35840
	ds_read_b128 v[204:207], v191 offset:36864
	ds_read_b128 v[208:211], v191 offset:37888
	ds_read_b128 v[212:215], v191 offset:38912
	ds_read_b128 v[216:219], v191 offset:39936
	global_load_lds_dwordx4 v[226:227], off
	v_lshl_add_u64 v[226:227], s[22:23], 0, v[156:157]
	s_mov_b32 m0, s46
	s_nop 0
	global_load_lds_dwordx4 v[226:227], off
	s_waitcnt vmcnt(8)
	s_waitcnt lgkmcnt(0)
	s_barrier
	s_setprio 1
	s_waitcnt lgkmcnt(0)
	v_mfma_f32_16x16x32_bf16 v[124:127], v[128:131], v[176:179], v[124:127]
	v_mfma_f32_16x16x32_bf16 v[120:123], v[136:139], v[176:179], v[120:123]
	v_mfma_f32_16x16x32_bf16 v[108:111], v[128:131], v[194:197], v[108:111]
	v_mfma_f32_16x16x32_bf16 v[104:107], v[136:139], v[194:197], v[104:107]
	v_mfma_f32_16x16x32_bf16 v[92:95], v[128:131], v[204:207], v[92:95]
	v_mfma_f32_16x16x32_bf16 v[88:91], v[136:139], v[204:207], v[88:91]
	v_mfma_f32_16x16x32_bf16 v[76:79], v[128:131], v[212:215], v[76:79]
	v_mfma_f32_16x16x32_bf16 v[72:75], v[136:139], v[212:215], v[72:75]
	v_mfma_f32_16x16x32_bf16 v[124:127], v[132:135], v[180:183], v[124:127]
	v_mfma_f32_16x16x32_bf16 v[120:123], v[140:143], v[180:183], v[120:123]
	v_mfma_f32_16x16x32_bf16 v[108:111], v[132:135], v[198:201], v[108:111]
	v_mfma_f32_16x16x32_bf16 v[104:107], v[140:143], v[198:201], v[104:107]
	v_mfma_f32_16x16x32_bf16 v[92:95], v[132:135], v[208:211], v[92:95]
	v_mfma_f32_16x16x32_bf16 v[88:91], v[140:143], v[208:211], v[88:91]
	v_mfma_f32_16x16x32_bf16 v[76:79], v[132:135], v[216:219], v[76:79]
	v_mfma_f32_16x16x32_bf16 v[72:75], v[140:143], v[216:219], v[72:75]
	s_setprio 0
	s_setprio 1
	v_mfma_f32_16x16x32_bf16 v[116:119], v[144:147], v[176:179], v[116:119]
	v_mfma_f32_16x16x32_bf16 v[112:115], v[168:171], v[176:179], v[112:115]
	v_mfma_f32_16x16x32_bf16 v[100:103], v[144:147], v[194:197], v[100:103]
	v_mfma_f32_16x16x32_bf16 v[96:99], v[168:171], v[194:197], v[96:99]
	v_mfma_f32_16x16x32_bf16 v[84:87], v[144:147], v[204:207], v[84:87]
	v_mfma_f32_16x16x32_bf16 v[80:83], v[168:171], v[204:207], v[80:83]
	v_mfma_f32_16x16x32_bf16 v[68:71], v[144:147], v[212:215], v[68:71]
	v_mfma_f32_16x16x32_bf16 v[64:67], v[168:171], v[212:215], v[64:67]
	v_mfma_f32_16x16x32_bf16 v[116:119], v[148:151], v[180:183], v[116:119]
	v_mfma_f32_16x16x32_bf16 v[112:115], v[172:175], v[180:183], v[112:115]
	v_mfma_f32_16x16x32_bf16 v[100:103], v[148:151], v[198:201], v[100:103]
	v_mfma_f32_16x16x32_bf16 v[96:99], v[172:175], v[198:201], v[96:99]
	s_barrier
	v_mfma_f32_16x16x32_bf16 v[84:87], v[148:151], v[208:211], v[84:87]
	v_mfma_f32_16x16x32_bf16 v[80:83], v[172:175], v[208:211], v[80:83]
	v_mfma_f32_16x16x32_bf16 v[68:71], v[148:151], v[216:219], v[68:71]
	v_mfma_f32_16x16x32_bf16 v[64:67], v[172:175], v[216:219], v[64:67]
	s_setprio 0
	s_add_i32 s22, s58, s42
	v_lshl_add_u64 v[184:185], v[184:185], 0, s[30:31]
	s_mov_b32 m0, s22
	ds_read_b128 v[176:179], v191 offset:49152
	ds_read_b128 v[180:183], v191 offset:50176
	ds_read_b128 v[194:197], v191 offset:51200
	ds_read_b128 v[198:201], v191 offset:52224
	ds_read_b128 v[204:207], v191 offset:53248
	ds_read_b128 v[208:211], v191 offset:54272
	ds_read_b128 v[212:215], v191 offset:55296
	ds_read_b128 v[216:219], v191 offset:56320
	global_load_lds_dwordx4 v[184:185], off
	s_add_i32 m0, s22, 0x2000
	s_add_u32 s22, s38, 0xb0080
	v_lshl_add_u64 v[184:185], v[220:221], 0, s[30:31]
	s_addc_u32 s23, s39, 0
	s_add_i32 s38, s59, s42
	global_load_lds_dwordx4 v[184:185], off
	v_lshl_add_u64 v[184:185], s[22:23], 0, v[154:155]
	s_mov_b32 m0, s38
	s_nop 0
	global_load_lds_dwordx4 v[184:185], off
	v_lshl_add_u64 v[184:185], s[22:23], 0, v[158:159]
	s_add_i32 m0, s38, 0x2000
	s_nop 0
	global_load_lds_dwordx4 v[184:185], off
	v_lshl_add_u64 v[184:185], v[222:223], 0, s[30:31]
	s_mov_b32 m0, s33
	s_nop 0
	global_load_lds_dwordx4 v[184:185], off
	v_lshl_add_u64 v[184:185], v[224:225], 0, s[30:31]
	s_mov_b32 m0, s48
	s_nop 0
	global_load_lds_dwordx4 v[184:185], off
	s_waitcnt vmcnt(8)
	s_waitcnt lgkmcnt(0)
	s_barrier
	s_setprio 1
	s_waitcnt lgkmcnt(0)
	v_mfma_f32_16x16x32_bf16 v[60:63], v[128:131], v[176:179], v[60:63]
	v_mfma_f32_16x16x32_bf16 v[56:59], v[136:139], v[176:179], v[56:59]
	v_mfma_f32_16x16x32_bf16 v[44:47], v[128:131], v[194:197], v[44:47]
	v_mfma_f32_16x16x32_bf16 v[40:43], v[136:139], v[194:197], v[40:43]
	v_mfma_f32_16x16x32_bf16 v[28:31], v[128:131], v[204:207], v[28:31]
	v_mfma_f32_16x16x32_bf16 v[24:27], v[136:139], v[204:207], v[24:27]
	v_mfma_f32_16x16x32_bf16 v[12:15], v[128:131], v[212:215], v[12:15]
	v_mfma_f32_16x16x32_bf16 v[8:11], v[136:139], v[212:215], v[8:11]
	v_mfma_f32_16x16x32_bf16 v[60:63], v[132:135], v[180:183], v[60:63]
	v_mfma_f32_16x16x32_bf16 v[56:59], v[140:143], v[180:183], v[56:59]
	v_mfma_f32_16x16x32_bf16 v[44:47], v[132:135], v[198:201], v[44:47]
	v_mfma_f32_16x16x32_bf16 v[40:43], v[140:143], v[198:201], v[40:43]
	v_mfma_f32_16x16x32_bf16 v[28:31], v[132:135], v[208:211], v[28:31]
	v_mfma_f32_16x16x32_bf16 v[24:27], v[140:143], v[208:211], v[24:27]
	v_mfma_f32_16x16x32_bf16 v[12:15], v[132:135], v[216:219], v[12:15]
	v_mfma_f32_16x16x32_bf16 v[8:11], v[140:143], v[216:219], v[8:11]
	s_setprio 0
	s_setprio 1
	v_mfma_f32_16x16x32_bf16 v[52:55], v[144:147], v[176:179], v[52:55]
	v_mfma_f32_16x16x32_bf16 v[48:51], v[168:171], v[176:179], v[48:51]
	v_mfma_f32_16x16x32_bf16 v[36:39], v[144:147], v[194:197], v[36:39]
	v_mfma_f32_16x16x32_bf16 v[32:35], v[168:171], v[194:197], v[32:35]
	v_mfma_f32_16x16x32_bf16 v[20:23], v[144:147], v[204:207], v[20:23]
	v_mfma_f32_16x16x32_bf16 v[16:19], v[168:171], v[204:207], v[16:19]
	v_mfma_f32_16x16x32_bf16 v[4:7], v[144:147], v[212:215], v[4:7]
	v_mfma_f32_16x16x32_bf16 v[0:3], v[168:171], v[212:215], v[0:3]
	v_mfma_f32_16x16x32_bf16 v[52:55], v[148:151], v[180:183], v[52:55]
	v_mfma_f32_16x16x32_bf16 v[48:51], v[172:175], v[180:183], v[48:51]
	v_mfma_f32_16x16x32_bf16 v[36:39], v[148:151], v[198:201], v[36:39]
	v_mfma_f32_16x16x32_bf16 v[32:35], v[172:175], v[198:201], v[32:35]
	s_barrier
	v_mfma_f32_16x16x32_bf16 v[20:23], v[148:151], v[208:211], v[20:23]
	v_mfma_f32_16x16x32_bf16 v[16:19], v[172:175], v[208:211], v[16:19]
	v_mfma_f32_16x16x32_bf16 v[4:7], v[148:151], v[216:219], v[4:7]
	v_mfma_f32_16x16x32_bf16 v[0:3], v[172:175], v[216:219], v[0:3]
	s_setprio 0
	s_add_i32 s57, s57, 2
	s_add_u32 s55, s55, 0x100
	s_addc_u32 s56, s56, 0
	s_cmp_gt_u32 s57, 41
	s_mov_b64 s[22:23], s[4:5]
	s_cbranch_scc0 .LBB0_559
	s_and_b64 vcc, exec, s[34:35]
	s_cbranch_vccz .LBB0_562
	s_barrier

.LBB0_643:
	ds_read_b128 v[128:131], v191
	ds_read_b128 v[132:135], v191 offset:1024
	ds_read_b128 v[156:159], v191 offset:2048
	ds_read_b128 v[160:163], v191 offset:3072
	ds_read_b128 v[164:167], v192
	ds_read_b128 v[168:171], v192 offset:1024
	ds_read_b128 v[172:175], v192 offset:2048
	ds_read_b128 v[176:179], v192 offset:3072
	s_add_u32 s4, s22, 0xfffc0080
	s_addc_u32 s5, s23, -1
	s_cmp_eq_u32 s63, 12
	s_cselect_b32 s47, s13, s5
	s_cselect_b32 s46, s17, s4
	s_cselect_b32 s5, s33, s62
	s_cselect_b32 s4, s39, s41
	v_lshl_add_u64 v[224:225], s[22:23], 0, v[148:149]
	s_add_i32 m0, s49, 0xc000
	ds_read_b128 v[180:183], v193
	ds_read_b128 v[184:187], v193 offset:1024
	ds_read_b128 v[198:201], v193 offset:2048
	ds_read_b128 v[204:207], v193 offset:3072
	ds_read_b128 v[208:211], v193 offset:4096
	ds_read_b128 v[212:215], v193 offset:5120
	ds_read_b128 v[216:219], v193 offset:6144
	ds_read_b128 v[220:223], v193 offset:7168
	global_load_lds_dwordx4 v[224:225], off
	v_lshl_add_u64 v[224:225], s[22:23], 0, v[150:151]
	s_add_i32 m0, s49, 0xe000
	s_nop 0
	global_load_lds_dwordx4 v[224:225], off
	s_waitcnt vmcnt(8)
	s_waitcnt lgkmcnt(0)
	s_barrier
	s_setprio 1
	s_waitcnt lgkmcnt(0)
	v_mfma_f32_16x16x32_bf16 v[124:127], v[128:131], v[180:183], v[124:127]
	v_mfma_f32_16x16x32_bf16 v[120:123], v[156:159], v[180:183], v[120:123]
	v_mfma_f32_16x16x32_bf16 v[108:111], v[128:131], v[198:201], v[108:111]
	v_mfma_f32_16x16x32_bf16 v[104:107], v[156:159], v[198:201], v[104:107]
	v_mfma_f32_16x16x32_bf16 v[92:95], v[128:131], v[208:211], v[92:95]
	v_mfma_f32_16x16x32_bf16 v[88:91], v[156:159], v[208:211], v[88:91]
	v_mfma_f32_16x16x32_bf16 v[76:79], v[128:131], v[216:219], v[76:79]
	v_mfma_f32_16x16x32_bf16 v[72:75], v[156:159], v[216:219], v[72:75]
	v_mfma_f32_16x16x32_bf16 v[124:127], v[132:135], v[184:187], v[124:127]
	v_mfma_f32_16x16x32_bf16 v[120:123], v[160:163], v[184:187], v[120:123]
	v_mfma_f32_16x16x32_bf16 v[108:111], v[132:135], v[204:207], v[108:111]
	v_mfma_f32_16x16x32_bf16 v[104:107], v[160:163], v[204:207], v[104:107]
	v_mfma_f32_16x16x32_bf16 v[92:95], v[132:135], v[212:215], v[92:95]
	v_mfma_f32_16x16x32_bf16 v[88:91], v[160:163], v[212:215], v[88:91]
	v_mfma_f32_16x16x32_bf16 v[76:79], v[132:135], v[220:223], v[76:79]
	v_mfma_f32_16x16x32_bf16 v[72:75], v[160:163], v[220:223], v[72:75]
	s_setprio 0
	s_setprio 1
	v_mfma_f32_16x16x32_bf16 v[116:119], v[164:167], v[180:183], v[116:119]
	v_mfma_f32_16x16x32_bf16 v[112:115], v[172:175], v[180:183], v[112:115]
	v_mfma_f32_16x16x32_bf16 v[100:103], v[164:167], v[198:201], v[100:103]
	v_mfma_f32_16x16x32_bf16 v[96:99], v[172:175], v[198:201], v[96:99]
	v_mfma_f32_16x16x32_bf16 v[84:87], v[164:167], v[208:211], v[84:87]
	v_mfma_f32_16x16x32_bf16 v[80:83], v[172:175], v[208:211], v[80:83]
	v_mfma_f32_16x16x32_bf16 v[68:71], v[164:167], v[216:219], v[68:71]
	v_mfma_f32_16x16x32_bf16 v[64:67], v[172:175], v[216:219], v[64:67]
	v_mfma_f32_16x16x32_bf16 v[116:119], v[168:171], v[184:187], v[116:119]
	v_mfma_f32_16x16x32_bf16 v[112:115], v[176:179], v[184:187], v[112:115]
	v_mfma_f32_16x16x32_bf16 v[100:103], v[168:171], v[204:207], v[100:103]
	v_mfma_f32_16x16x32_bf16 v[96:99], v[176:179], v[204:207], v[96:99]
	s_barrier
	v_mfma_f32_16x16x32_bf16 v[84:87], v[168:171], v[212:215], v[84:87]
	v_mfma_f32_16x16x32_bf16 v[80:83], v[176:179], v[212:215], v[80:83]
	v_mfma_f32_16x16x32_bf16 v[68:71], v[168:171], v[220:223], v[68:71]
	v_mfma_f32_16x16x32_bf16 v[64:67], v[176:179], v[220:223], v[64:67]
	s_setprio 0
	s_add_i32 s64, s59, s48
	v_lshl_add_u64 v[224:225], s[4:5], 0, v[138:139]
	s_mov_b32 m0, s64
	ds_read_b128 v[180:183], v193 offset:16384
	ds_read_b128 v[184:187], v193 offset:17408
	ds_read_b128 v[198:201], v193 offset:18432
	ds_read_b128 v[204:207], v193 offset:19456
	ds_read_b128 v[208:211], v193 offset:20480
	ds_read_b128 v[212:215], v193 offset:21504
	ds_read_b128 v[216:219], v193 offset:22528
	ds_read_b128 v[220:223], v193 offset:23552
	global_load_lds_dwordx4 v[224:225], off
	s_add_i32 m0, s64, 0x2000
	s_add_u32 s64, s4, 0x40000
	v_lshl_add_u64 v[226:227], s[4:5], 0, v[142:143]
	s_addc_u32 s65, s5, 0
	s_add_i32 s66, s60, s48
	global_load_lds_dwordx4 v[226:227], off
	v_lshl_add_u64 v[228:229], s[64:65], 0, v[138:139]
	s_mov_b32 m0, s66
	v_lshl_add_u64 v[230:231], s[46:47], 0, v[140:141]
	global_load_lds_dwordx4 v[228:229], off
	v_lshl_add_u64 v[228:229], s[64:65], 0, v[142:143]
	s_add_i32 m0, s66, 0x2000
	s_nop 0
	global_load_lds_dwordx4 v[228:229], off
	v_lshl_add_u64 v[228:229], s[46:47], 0, v[136:137]
	s_mov_b32 m0, s49
	s_nop 0
	global_load_lds_dwordx4 v[228:229], off
	s_mov_b32 m0, s50
	s_nop 0
	global_load_lds_dwordx4 v[230:231], off
	s_waitcnt vmcnt(8)
	s_waitcnt lgkmcnt(0)
	s_barrier
	s_setprio 1
	s_waitcnt lgkmcnt(0)
	v_mfma_f32_16x16x32_bf16 v[60:63], v[128:131], v[180:183], v[60:63]
	v_mfma_f32_16x16x32_bf16 v[56:59], v[156:159], v[180:183], v[56:59]
	v_mfma_f32_16x16x32_bf16 v[44:47], v[128:131], v[198:201], v[44:47]
	v_mfma_f32_16x16x32_bf16 v[40:43], v[156:159], v[198:201], v[40:43]
	v_mfma_f32_16x16x32_bf16 v[28:31], v[128:131], v[208:211], v[28:31]
	v_mfma_f32_16x16x32_bf16 v[24:27], v[156:159], v[208:211], v[24:27]
	v_mfma_f32_16x16x32_bf16 v[12:15], v[128:131], v[216:219], v[12:15]
	v_mfma_f32_16x16x32_bf16 v[8:11], v[156:159], v[216:219], v[8:11]
	v_mfma_f32_16x16x32_bf16 v[60:63], v[132:135], v[184:187], v[60:63]
	v_mfma_f32_16x16x32_bf16 v[56:59], v[160:163], v[184:187], v[56:59]
	v_mfma_f32_16x16x32_bf16 v[44:47], v[132:135], v[204:207], v[44:47]
	v_mfma_f32_16x16x32_bf16 v[40:43], v[160:163], v[204:207], v[40:43]
	v_mfma_f32_16x16x32_bf16 v[28:31], v[132:135], v[212:215], v[28:31]
	v_mfma_f32_16x16x32_bf16 v[24:27], v[160:163], v[212:215], v[24:27]
	v_mfma_f32_16x16x32_bf16 v[12:15], v[132:135], v[220:223], v[12:15]
	v_mfma_f32_16x16x32_bf16 v[8:11], v[160:163], v[220:223], v[8:11]
	s_setprio 0
	s_setprio 1
	v_mfma_f32_16x16x32_bf16 v[52:55], v[164:167], v[180:183], v[52:55]
	v_mfma_f32_16x16x32_bf16 v[48:51], v[172:175], v[180:183], v[48:51]
	v_mfma_f32_16x16x32_bf16 v[36:39], v[164:167], v[198:201], v[36:39]
	v_mfma_f32_16x16x32_bf16 v[32:35], v[172:175], v[198:201], v[32:35]
	v_mfma_f32_16x16x32_bf16 v[20:23], v[164:167], v[208:211], v[20:23]
	v_mfma_f32_16x16x32_bf16 v[16:19], v[172:175], v[208:211], v[16:19]
	v_mfma_f32_16x16x32_bf16 v[4:7], v[164:167], v[216:219], v[4:7]
	v_mfma_f32_16x16x32_bf16 v[0:3], v[172:175], v[216:219], v[0:3]
	v_mfma_f32_16x16x32_bf16 v[52:55], v[168:171], v[184:187], v[52:55]
	v_mfma_f32_16x16x32_bf16 v[48:51], v[176:179], v[184:187], v[48:51]
	v_mfma_f32_16x16x32_bf16 v[36:39], v[168:171], v[204:207], v[36:39]
	v_mfma_f32_16x16x32_bf16 v[32:35], v[176:179], v[204:207], v[32:35]
	s_barrier
	v_mfma_f32_16x16x32_bf16 v[20:23], v[168:171], v[212:215], v[20:23]
	v_mfma_f32_16x16x32_bf16 v[16:19], v[176:179], v[212:215], v[16:19]
	v_mfma_f32_16x16x32_bf16 v[4:7], v[168:171], v[220:223], v[4:7]
	v_mfma_f32_16x16x32_bf16 v[0:3], v[176:179], v[220:223], v[0:3]
	s_setprio 0
	s_add_i32 s64, 0, 0x18000
	v_add_u32_e32 v144, s64, v189
	s_add_i32 s65, 0, 0x1c000
	ds_read_b128 v[128:131], v144
	ds_read_b128 v[132:135], v144 offset:1024
	ds_read_b128 v[156:159], v144 offset:2048
	ds_read_b128 v[160:163], v144 offset:3072
	v_add_u32_e32 v144, s65, v189
	ds_read_b128 v[164:167], v144
	ds_read_b128 v[168:171], v144 offset:1024
	ds_read_b128 v[172:175], v144 offset:2048
	ds_read_b128 v[176:179], v144 offset:3072
	s_add_u32 s46, s46, 0x40000
	s_addc_u32 s47, s47, 0
	s_mov_b32 m0, s51
	v_lshl_add_u64 v[232:233], s[46:47], 0, v[136:137]
	ds_read_b128 v[180:183], v193 offset:32768
	ds_read_b128 v[184:187], v193 offset:33792
	ds_read_b128 v[198:201], v193 offset:34816
	ds_read_b128 v[204:207], v193 offset:35840
	ds_read_b128 v[208:211], v193 offset:36864
	ds_read_b128 v[212:215], v193 offset:37888
	ds_read_b128 v[216:219], v193 offset:38912
	ds_read_b128 v[220:223], v193 offset:39936
	global_load_lds_dwordx4 v[232:233], off
	v_lshl_add_u64 v[232:233], s[46:47], 0, v[140:141]
	s_mov_b32 m0, s52
	s_nop 0
	global_load_lds_dwordx4 v[232:233], off
	s_waitcnt vmcnt(8)
	s_waitcnt lgkmcnt(0)
	s_barrier
	s_setprio 1
	s_waitcnt lgkmcnt(0)
	v_mfma_f32_16x16x32_bf16 v[124:127], v[128:131], v[180:183], v[124:127]
	v_mfma_f32_16x16x32_bf16 v[120:123], v[156:159], v[180:183], v[120:123]
	v_mfma_f32_16x16x32_bf16 v[108:111], v[128:131], v[198:201], v[108:111]
	v_mfma_f32_16x16x32_bf16 v[104:107], v[156:159], v[198:201], v[104:107]
	v_mfma_f32_16x16x32_bf16 v[92:95], v[128:131], v[208:211], v[92:95]
	v_mfma_f32_16x16x32_bf16 v[88:91], v[156:159], v[208:211], v[88:91]
	v_mfma_f32_16x16x32_bf16 v[76:79], v[128:131], v[216:219], v[76:79]
	v_mfma_f32_16x16x32_bf16 v[72:75], v[156:159], v[216:219], v[72:75]
	v_mfma_f32_16x16x32_bf16 v[124:127], v[132:135], v[184:187], v[124:127]
	v_mfma_f32_16x16x32_bf16 v[120:123], v[160:163], v[184:187], v[120:123]
	v_mfma_f32_16x16x32_bf16 v[108:111], v[132:135], v[204:207], v[108:111]
	v_mfma_f32_16x16x32_bf16 v[104:107], v[160:163], v[204:207], v[104:107]
	v_mfma_f32_16x16x32_bf16 v[92:95], v[132:135], v[212:215], v[92:95]
	v_mfma_f32_16x16x32_bf16 v[88:91], v[160:163], v[212:215], v[88:91]
	v_mfma_f32_16x16x32_bf16 v[76:79], v[132:135], v[220:223], v[76:79]
	v_mfma_f32_16x16x32_bf16 v[72:75], v[160:163], v[220:223], v[72:75]
	s_setprio 0
	s_setprio 1
	v_mfma_f32_16x16x32_bf16 v[116:119], v[164:167], v[180:183], v[116:119]
	v_mfma_f32_16x16x32_bf16 v[112:115], v[172:175], v[180:183], v[112:115]
	v_mfma_f32_16x16x32_bf16 v[100:103], v[164:167], v[198:201], v[100:103]
	v_mfma_f32_16x16x32_bf16 v[96:99], v[172:175], v[198:201], v[96:99]
	v_mfma_f32_16x16x32_bf16 v[84:87], v[164:167], v[208:211], v[84:87]
	v_mfma_f32_16x16x32_bf16 v[80:83], v[172:175], v[208:211], v[80:83]
	v_mfma_f32_16x16x32_bf16 v[68:71], v[164:167], v[216:219], v[68:71]
	v_mfma_f32_16x16x32_bf16 v[64:67], v[172:175], v[216:219], v[64:67]
	v_mfma_f32_16x16x32_bf16 v[116:119], v[168:171], v[184:187], v[116:119]
	v_mfma_f32_16x16x32_bf16 v[112:115], v[176:179], v[184:187], v[112:115]
	v_mfma_f32_16x16x32_bf16 v[100:103], v[168:171], v[204:207], v[100:103]
	v_mfma_f32_16x16x32_bf16 v[96:99], v[176:179], v[204:207], v[96:99]
	s_barrier
	v_mfma_f32_16x16x32_bf16 v[84:87], v[168:171], v[212:215], v[84:87]
	v_mfma_f32_16x16x32_bf16 v[80:83], v[176:179], v[212:215], v[80:83]
	v_mfma_f32_16x16x32_bf16 v[68:71], v[168:171], v[220:223], v[68:71]
	v_mfma_f32_16x16x32_bf16 v[64:67], v[176:179], v[220:223], v[64:67]
	s_setprio 0
	s_add_i32 s46, s64, s48
	v_lshl_add_u64 v[224:225], v[224:225], 0, s[30:31]
	s_mov_b32 m0, s46
	ds_read_b128 v[180:183], v193 offset:49152
	ds_read_b128 v[184:187], v193 offset:50176
	ds_read_b128 v[198:201], v193 offset:51200
	ds_read_b128 v[204:207], v193 offset:52224
	ds_read_b128 v[208:211], v193 offset:53248
	ds_read_b128 v[212:215], v193 offset:54272
	ds_read_b128 v[216:219], v193 offset:55296
	ds_read_b128 v[220:223], v193 offset:56320
	global_load_lds_dwordx4 v[224:225], off
	s_add_i32 m0, s46, 0x2000
	s_add_u32 s4, s4, 0x40080
	v_lshl_add_u64 v[224:225], v[226:227], 0, s[30:31]
	s_addc_u32 s5, s5, 0
	s_add_i32 s46, s65, s48
	global_load_lds_dwordx4 v[224:225], off
	v_lshl_add_u64 v[224:225], s[4:5], 0, v[138:139]
	s_mov_b32 m0, s46
	s_nop 0
	global_load_lds_dwordx4 v[224:225], off
	v_lshl_add_u64 v[224:225], s[4:5], 0, v[142:143]
	s_add_i32 m0, s46, 0x2000
	s_nop 0
	global_load_lds_dwordx4 v[224:225], off
	v_lshl_add_u64 v[224:225], v[228:229], 0, s[30:31]
	s_mov_b32 m0, s56
	s_nop 0
	global_load_lds_dwordx4 v[224:225], off
	v_lshl_add_u64 v[224:225], v[230:231], 0, s[30:31]
	s_mov_b32 m0, s57
	s_nop 0
	global_load_lds_dwordx4 v[224:225], off
	s_waitcnt vmcnt(8)
	s_waitcnt lgkmcnt(0)
	s_barrier
	s_setprio 1
	s_waitcnt lgkmcnt(0)
	v_mfma_f32_16x16x32_bf16 v[60:63], v[128:131], v[180:183], v[60:63]
	v_mfma_f32_16x16x32_bf16 v[56:59], v[156:159], v[180:183], v[56:59]
	v_mfma_f32_16x16x32_bf16 v[44:47], v[128:131], v[198:201], v[44:47]
	v_mfma_f32_16x16x32_bf16 v[40:43], v[156:159], v[198:201], v[40:43]
	v_mfma_f32_16x16x32_bf16 v[28:31], v[128:131], v[208:211], v[28:31]
	v_mfma_f32_16x16x32_bf16 v[24:27], v[156:159], v[208:211], v[24:27]
	v_mfma_f32_16x16x32_bf16 v[12:15], v[128:131], v[216:219], v[12:15]
	v_mfma_f32_16x16x32_bf16 v[8:11], v[156:159], v[216:219], v[8:11]
	v_mfma_f32_16x16x32_bf16 v[60:63], v[132:135], v[184:187], v[60:63]
	v_mfma_f32_16x16x32_bf16 v[56:59], v[160:163], v[184:187], v[56:59]
	v_mfma_f32_16x16x32_bf16 v[44:47], v[132:135], v[204:207], v[44:47]
	v_mfma_f32_16x16x32_bf16 v[40:43], v[160:163], v[204:207], v[40:43]
	v_mfma_f32_16x16x32_bf16 v[28:31], v[132:135], v[212:215], v[28:31]
	v_mfma_f32_16x16x32_bf16 v[24:27], v[160:163], v[212:215], v[24:27]
	v_mfma_f32_16x16x32_bf16 v[12:15], v[132:135], v[220:223], v[12:15]
	v_mfma_f32_16x16x32_bf16 v[8:11], v[160:163], v[220:223], v[8:11]
	s_setprio 0
	s_setprio 1
	v_mfma_f32_16x16x32_bf16 v[52:55], v[164:167], v[180:183], v[52:55]
	v_mfma_f32_16x16x32_bf16 v[48:51], v[172:175], v[180:183], v[48:51]
	v_mfma_f32_16x16x32_bf16 v[36:39], v[164:167], v[198:201], v[36:39]
	v_mfma_f32_16x16x32_bf16 v[32:35], v[172:175], v[198:201], v[32:35]
	v_mfma_f32_16x16x32_bf16 v[20:23], v[164:167], v[208:211], v[20:23]
	v_mfma_f32_16x16x32_bf16 v[16:19], v[172:175], v[208:211], v[16:19]
	v_mfma_f32_16x16x32_bf16 v[4:7], v[164:167], v[216:219], v[4:7]
	v_mfma_f32_16x16x32_bf16 v[0:3], v[172:175], v[216:219], v[0:3]
	v_mfma_f32_16x16x32_bf16 v[52:55], v[168:171], v[184:187], v[52:55]
	v_mfma_f32_16x16x32_bf16 v[48:51], v[176:179], v[184:187], v[48:51]
	v_mfma_f32_16x16x32_bf16 v[36:39], v[168:171], v[204:207], v[36:39]
	v_mfma_f32_16x16x32_bf16 v[32:35], v[176:179], v[204:207], v[32:35]
	s_barrier
	v_mfma_f32_16x16x32_bf16 v[20:23], v[168:171], v[212:215], v[20:23]
	v_mfma_f32_16x16x32_bf16 v[16:19], v[176:179], v[212:215], v[16:19]
	v_mfma_f32_16x16x32_bf16 v[4:7], v[168:171], v[220:223], v[4:7]
	v_mfma_f32_16x16x32_bf16 v[0:3], v[176:179], v[220:223], v[0:3]
	s_setprio 0
	s_add_i32 s63, s63, 2
	s_add_u32 s22, s22, 0x100
	s_addc_u32 s23, s23, 0
	s_add_u32 s41, s41, 0x100
	s_addc_u32 s62, s62, 0
	s_cmp_gt_u32 s63, 13
	s_cbranch_scc0 .LBB0_643
	s_and_b64 vcc, exec, s[34:35]
	s_cbranch_vccz .LBB0_646
	s_barrier

.LBB0_966:
	ds_read_b128 v[128:131], v189
	ds_read_b128 v[132:135], v189 offset:1024
	ds_read_b128 v[136:139], v189 offset:2048
	ds_read_b128 v[140:143], v189 offset:3072
	ds_read_b128 v[144:147], v190
	ds_read_b128 v[148:151], v190 offset:1024
	ds_read_b128 v[168:171], v190 offset:2048
	ds_read_b128 v[172:175], v190 offset:3072
	s_add_u32 s4, s22, 0xfffc0080
	s_addc_u32 s5, s23, -1
	s_cmp_eq_u32 s58, 12
	s_cselect_b32 s43, s35, s5
	s_cselect_b32 s42, s41, s4
	s_cselect_b32 s5, s31, s57
	s_cselect_b32 s4, s55, s56
	v_lshl_add_u64 v[184:185], s[22:23], 0, v[160:161]
	s_add_i32 m0, s46, 0xc000
	ds_read_b128 v[176:179], v191
	ds_read_b128 v[180:183], v191 offset:1024
	ds_read_b128 v[192:195], v191 offset:2048
	ds_read_b128 v[198:201], v191 offset:3072
	ds_read_b128 v[204:207], v191 offset:4096
	ds_read_b128 v[208:211], v191 offset:5120
	ds_read_b128 v[212:215], v191 offset:6144
	ds_read_b128 v[216:219], v191 offset:7168
	global_load_lds_dwordx4 v[184:185], off
	v_lshl_add_u64 v[184:185], s[22:23], 0, v[162:163]
	s_add_i32 m0, s46, 0xe000
	s_nop 0
	global_load_lds_dwordx4 v[184:185], off
	s_waitcnt vmcnt(8)
	s_waitcnt lgkmcnt(0)
	s_barrier
	s_setprio 1
	s_waitcnt lgkmcnt(0)
	v_mfma_f32_16x16x32_bf16 v[124:127], v[128:131], v[176:179], v[124:127]
	v_mfma_f32_16x16x32_bf16 v[120:123], v[136:139], v[176:179], v[120:123]
	v_mfma_f32_16x16x32_bf16 v[108:111], v[128:131], v[192:195], v[108:111]
	v_mfma_f32_16x16x32_bf16 v[104:107], v[136:139], v[192:195], v[104:107]
	v_mfma_f32_16x16x32_bf16 v[92:95], v[128:131], v[204:207], v[92:95]
	v_mfma_f32_16x16x32_bf16 v[88:91], v[136:139], v[204:207], v[88:91]
	v_mfma_f32_16x16x32_bf16 v[76:79], v[128:131], v[212:215], v[76:79]
	v_mfma_f32_16x16x32_bf16 v[72:75], v[136:139], v[212:215], v[72:75]
	v_mfma_f32_16x16x32_bf16 v[124:127], v[132:135], v[180:183], v[124:127]
	v_mfma_f32_16x16x32_bf16 v[120:123], v[140:143], v[180:183], v[120:123]
	v_mfma_f32_16x16x32_bf16 v[108:111], v[132:135], v[198:201], v[108:111]
	v_mfma_f32_16x16x32_bf16 v[104:107], v[140:143], v[198:201], v[104:107]
	v_mfma_f32_16x16x32_bf16 v[92:95], v[132:135], v[208:211], v[92:95]
	v_mfma_f32_16x16x32_bf16 v[88:91], v[140:143], v[208:211], v[88:91]
	v_mfma_f32_16x16x32_bf16 v[76:79], v[132:135], v[216:219], v[76:79]
	v_mfma_f32_16x16x32_bf16 v[72:75], v[140:143], v[216:219], v[72:75]
	s_setprio 0
	s_setprio 1
	v_mfma_f32_16x16x32_bf16 v[116:119], v[144:147], v[176:179], v[116:119]
	v_mfma_f32_16x16x32_bf16 v[112:115], v[168:171], v[176:179], v[112:115]
	v_mfma_f32_16x16x32_bf16 v[100:103], v[144:147], v[192:195], v[100:103]
	v_mfma_f32_16x16x32_bf16 v[96:99], v[168:171], v[192:195], v[96:99]
	v_mfma_f32_16x16x32_bf16 v[84:87], v[144:147], v[204:207], v[84:87]
	v_mfma_f32_16x16x32_bf16 v[80:83], v[168:171], v[204:207], v[80:83]
	v_mfma_f32_16x16x32_bf16 v[68:71], v[144:147], v[212:215], v[68:71]
	v_mfma_f32_16x16x32_bf16 v[64:67], v[168:171], v[212:215], v[64:67]
	v_mfma_f32_16x16x32_bf16 v[116:119], v[148:151], v[180:183], v[116:119]
	v_mfma_f32_16x16x32_bf16 v[112:115], v[172:175], v[180:183], v[112:115]
	v_mfma_f32_16x16x32_bf16 v[100:103], v[148:151], v[198:201], v[100:103]
	v_mfma_f32_16x16x32_bf16 v[96:99], v[172:175], v[198:201], v[96:99]
	s_barrier
	v_mfma_f32_16x16x32_bf16 v[84:87], v[148:151], v[208:211], v[84:87]
	v_mfma_f32_16x16x32_bf16 v[80:83], v[172:175], v[208:211], v[80:83]
	v_mfma_f32_16x16x32_bf16 v[68:71], v[148:151], v[216:219], v[68:71]
	v_mfma_f32_16x16x32_bf16 v[64:67], v[172:175], v[216:219], v[64:67]
	s_setprio 0
	s_add_i32 s59, s52, s45
	v_lshl_add_u64 v[184:185], s[4:5], 0, v[154:155]
	s_mov_b32 m0, s59
	ds_read_b128 v[176:179], v191 offset:16384
	ds_read_b128 v[180:183], v191 offset:17408
	ds_read_b128 v[192:195], v191 offset:18432
	ds_read_b128 v[198:201], v191 offset:19456
	ds_read_b128 v[204:207], v191 offset:20480
	ds_read_b128 v[208:211], v191 offset:21504
	ds_read_b128 v[212:215], v191 offset:22528
	ds_read_b128 v[216:219], v191 offset:23552
	global_load_lds_dwordx4 v[184:185], off
	s_add_i32 m0, s59, 0x2000
	s_add_u32 s60, s4, 0x40000
	v_lshl_add_u64 v[220:221], s[4:5], 0, v[158:159]
	s_addc_u32 s61, s5, 0
	s_add_i32 s59, s53, s45
	global_load_lds_dwordx4 v[220:221], off
	v_lshl_add_u64 v[222:223], s[60:61], 0, v[154:155]
	s_mov_b32 m0, s59
	v_lshl_add_u64 v[224:225], s[42:43], 0, v[156:157]
	global_load_lds_dwordx4 v[222:223], off
	v_lshl_add_u64 v[222:223], s[60:61], 0, v[158:159]
	s_add_i32 m0, s59, 0x2000
	s_nop 0
	global_load_lds_dwordx4 v[222:223], off
	v_lshl_add_u64 v[222:223], s[42:43], 0, v[152:153]
	s_mov_b32 m0, s46
	s_nop 0
	global_load_lds_dwordx4 v[222:223], off
	s_mov_b32 m0, s33
	s_nop 0
	global_load_lds_dwordx4 v[224:225], off
	s_waitcnt vmcnt(8)
	s_waitcnt lgkmcnt(0)
	s_barrier
	s_setprio 1
	s_waitcnt lgkmcnt(0)
	v_mfma_f32_16x16x32_bf16 v[60:63], v[128:131], v[176:179], v[60:63]
	v_mfma_f32_16x16x32_bf16 v[56:59], v[136:139], v[176:179], v[56:59]
	v_mfma_f32_16x16x32_bf16 v[44:47], v[128:131], v[192:195], v[44:47]
	v_mfma_f32_16x16x32_bf16 v[40:43], v[136:139], v[192:195], v[40:43]
	v_mfma_f32_16x16x32_bf16 v[28:31], v[128:131], v[204:207], v[28:31]
	v_mfma_f32_16x16x32_bf16 v[24:27], v[136:139], v[204:207], v[24:27]
	v_mfma_f32_16x16x32_bf16 v[12:15], v[128:131], v[212:215], v[12:15]
	v_mfma_f32_16x16x32_bf16 v[8:11], v[136:139], v[212:215], v[8:11]
	v_mfma_f32_16x16x32_bf16 v[60:63], v[132:135], v[180:183], v[60:63]
	v_mfma_f32_16x16x32_bf16 v[56:59], v[140:143], v[180:183], v[56:59]
	v_mfma_f32_16x16x32_bf16 v[44:47], v[132:135], v[198:201], v[44:47]
	v_mfma_f32_16x16x32_bf16 v[40:43], v[140:143], v[198:201], v[40:43]
	v_mfma_f32_16x16x32_bf16 v[28:31], v[132:135], v[208:211], v[28:31]
	v_mfma_f32_16x16x32_bf16 v[24:27], v[140:143], v[208:211], v[24:27]
	v_mfma_f32_16x16x32_bf16 v[12:15], v[132:135], v[216:219], v[12:15]
	v_mfma_f32_16x16x32_bf16 v[8:11], v[140:143], v[216:219], v[8:11]
	s_setprio 0
	s_setprio 1
	v_mfma_f32_16x16x32_bf16 v[52:55], v[144:147], v[176:179], v[52:55]
	v_mfma_f32_16x16x32_bf16 v[48:51], v[168:171], v[176:179], v[48:51]
	v_mfma_f32_16x16x32_bf16 v[36:39], v[144:147], v[192:195], v[36:39]
	v_mfma_f32_16x16x32_bf16 v[32:35], v[168:171], v[192:195], v[32:35]
	v_mfma_f32_16x16x32_bf16 v[20:23], v[144:147], v[204:207], v[20:23]
	v_mfma_f32_16x16x32_bf16 v[16:19], v[168:171], v[204:207], v[16:19]
	v_mfma_f32_16x16x32_bf16 v[4:7], v[144:147], v[212:215], v[4:7]
	v_mfma_f32_16x16x32_bf16 v[0:3], v[168:171], v[212:215], v[0:3]
	v_mfma_f32_16x16x32_bf16 v[52:55], v[148:151], v[180:183], v[52:55]
	v_mfma_f32_16x16x32_bf16 v[48:51], v[172:175], v[180:183], v[48:51]
	v_mfma_f32_16x16x32_bf16 v[36:39], v[148:151], v[198:201], v[36:39]
	v_mfma_f32_16x16x32_bf16 v[32:35], v[172:175], v[198:201], v[32:35]
	s_barrier
	v_mfma_f32_16x16x32_bf16 v[20:23], v[148:151], v[208:211], v[20:23]
	v_mfma_f32_16x16x32_bf16 v[16:19], v[172:175], v[208:211], v[16:19]
	v_mfma_f32_16x16x32_bf16 v[4:7], v[148:151], v[216:219], v[4:7]
	v_mfma_f32_16x16x32_bf16 v[0:3], v[172:175], v[216:219], v[0:3]
	s_setprio 0
	s_add_i32 s59, 0, 0x18000
	s_add_i32 s60, 0, 0x1c000
	v_add_u32_e32 v140, s59, v187
	v_add_u32_e32 v172, s60, v187
	ds_read_b128 v[128:131], v140
	ds_read_b128 v[132:135], v140 offset:1024
	ds_read_b128 v[136:139], v140 offset:2048
	ds_read_b128 v[140:143], v140 offset:3072
	ds_read_b128 v[144:147], v172
	ds_read_b128 v[148:151], v172 offset:1024
	ds_read_b128 v[168:171], v172 offset:2048
	ds_read_b128 v[172:175], v172 offset:3072
	s_add_u32 s42, s42, 0x40000
	s_addc_u32 s43, s43, 0
	s_mov_b32 m0, s47
	v_lshl_add_u64 v[226:227], s[42:43], 0, v[152:153]
	ds_read_b128 v[176:179], v191 offset:32768
	ds_read_b128 v[180:183], v191 offset:33792
	ds_read_b128 v[192:195], v191 offset:34816
	ds_read_b128 v[198:201], v191 offset:35840
	ds_read_b128 v[204:207], v191 offset:36864
	ds_read_b128 v[208:211], v191 offset:37888
	ds_read_b128 v[212:215], v191 offset:38912
	ds_read_b128 v[216:219], v191 offset:39936
	global_load_lds_dwordx4 v[226:227], off
	v_lshl_add_u64 v[226:227], s[42:43], 0, v[156:157]
	s_mov_b32 m0, s48
	s_nop 0
	global_load_lds_dwordx4 v[226:227], off
	s_waitcnt vmcnt(8)
	s_waitcnt lgkmcnt(0)
	s_barrier
	s_setprio 1
	s_waitcnt lgkmcnt(0)
	v_mfma_f32_16x16x32_bf16 v[124:127], v[128:131], v[176:179], v[124:127]
	v_mfma_f32_16x16x32_bf16 v[120:123], v[136:139], v[176:179], v[120:123]
	v_mfma_f32_16x16x32_bf16 v[108:111], v[128:131], v[192:195], v[108:111]
	v_mfma_f32_16x16x32_bf16 v[104:107], v[136:139], v[192:195], v[104:107]
	v_mfma_f32_16x16x32_bf16 v[92:95], v[128:131], v[204:207], v[92:95]
	v_mfma_f32_16x16x32_bf16 v[88:91], v[136:139], v[204:207], v[88:91]
	v_mfma_f32_16x16x32_bf16 v[76:79], v[128:131], v[212:215], v[76:79]
	v_mfma_f32_16x16x32_bf16 v[72:75], v[136:139], v[212:215], v[72:75]
	v_mfma_f32_16x16x32_bf16 v[124:127], v[132:135], v[180:183], v[124:127]
	v_mfma_f32_16x16x32_bf16 v[120:123], v[140:143], v[180:183], v[120:123]
	v_mfma_f32_16x16x32_bf16 v[108:111], v[132:135], v[198:201], v[108:111]
	v_mfma_f32_16x16x32_bf16 v[104:107], v[140:143], v[198:201], v[104:107]
	v_mfma_f32_16x16x32_bf16 v[92:95], v[132:135], v[208:211], v[92:95]
	v_mfma_f32_16x16x32_bf16 v[88:91], v[140:143], v[208:211], v[88:91]
	v_mfma_f32_16x16x32_bf16 v[76:79], v[132:135], v[216:219], v[76:79]
	v_mfma_f32_16x16x32_bf16 v[72:75], v[140:143], v[216:219], v[72:75]
	s_setprio 0
	s_setprio 1
	v_mfma_f32_16x16x32_bf16 v[116:119], v[144:147], v[176:179], v[116:119]
	v_mfma_f32_16x16x32_bf16 v[112:115], v[168:171], v[176:179], v[112:115]
	v_mfma_f32_16x16x32_bf16 v[100:103], v[144:147], v[192:195], v[100:103]
	v_mfma_f32_16x16x32_bf16 v[96:99], v[168:171], v[192:195], v[96:99]
	v_mfma_f32_16x16x32_bf16 v[84:87], v[144:147], v[204:207], v[84:87]
	v_mfma_f32_16x16x32_bf16 v[80:83], v[168:171], v[204:207], v[80:83]
	v_mfma_f32_16x16x32_bf16 v[68:71], v[144:147], v[212:215], v[68:71]
	v_mfma_f32_16x16x32_bf16 v[64:67], v[168:171], v[212:215], v[64:67]
	v_mfma_f32_16x16x32_bf16 v[116:119], v[148:151], v[180:183], v[116:119]
	v_mfma_f32_16x16x32_bf16 v[112:115], v[172:175], v[180:183], v[112:115]
	v_mfma_f32_16x16x32_bf16 v[100:103], v[148:151], v[198:201], v[100:103]
	v_mfma_f32_16x16x32_bf16 v[96:99], v[172:175], v[198:201], v[96:99]
	s_barrier
	v_mfma_f32_16x16x32_bf16 v[84:87], v[148:151], v[208:211], v[84:87]
	v_mfma_f32_16x16x32_bf16 v[80:83], v[172:175], v[208:211], v[80:83]
	v_mfma_f32_16x16x32_bf16 v[68:71], v[148:151], v[216:219], v[68:71]
	v_mfma_f32_16x16x32_bf16 v[64:67], v[172:175], v[216:219], v[64:67]
	s_setprio 0
	s_add_i32 s42, s59, s45
	v_lshl_add_u64 v[184:185], v[184:185], 0, s[26:27]
	s_mov_b32 m0, s42
	ds_read_b128 v[176:179], v191 offset:49152
	ds_read_b128 v[180:183], v191 offset:50176
	ds_read_b128 v[192:195], v191 offset:51200
	ds_read_b128 v[198:201], v191 offset:52224
	ds_read_b128 v[204:207], v191 offset:53248
	ds_read_b128 v[208:211], v191 offset:54272
	ds_read_b128 v[212:215], v191 offset:55296
	ds_read_b128 v[216:219], v191 offset:56320
	global_load_lds_dwordx4 v[184:185], off
	s_add_i32 m0, s42, 0x2000
	s_add_u32 s4, s4, 0x40080
	v_lshl_add_u64 v[184:185], v[220:221], 0, s[26:27]
	s_addc_u32 s5, s5, 0
	s_add_i32 s42, s60, s45
	global_load_lds_dwordx4 v[184:185], off
	v_lshl_add_u64 v[184:185], s[4:5], 0, v[154:155]
	s_mov_b32 m0, s42
	s_nop 0
	global_load_lds_dwordx4 v[184:185], off
	v_lshl_add_u64 v[184:185], s[4:5], 0, v[158:159]
	s_add_i32 m0, s42, 0x2000
	s_nop 0
	global_load_lds_dwordx4 v[184:185], off
	v_lshl_add_u64 v[184:185], v[222:223], 0, s[26:27]
	s_mov_b32 m0, s50
	s_nop 0
	global_load_lds_dwordx4 v[184:185], off
	v_lshl_add_u64 v[184:185], v[224:225], 0, s[26:27]
	s_mov_b32 m0, s51
	s_nop 0
	global_load_lds_dwordx4 v[184:185], off
	s_waitcnt vmcnt(8)
	s_waitcnt lgkmcnt(0)
	s_barrier
	s_setprio 1
	s_waitcnt lgkmcnt(0)
	v_mfma_f32_16x16x32_bf16 v[60:63], v[128:131], v[176:179], v[60:63]
	v_mfma_f32_16x16x32_bf16 v[56:59], v[136:139], v[176:179], v[56:59]
	v_mfma_f32_16x16x32_bf16 v[44:47], v[128:131], v[192:195], v[44:47]
	v_mfma_f32_16x16x32_bf16 v[40:43], v[136:139], v[192:195], v[40:43]
	v_mfma_f32_16x16x32_bf16 v[28:31], v[128:131], v[204:207], v[28:31]
	v_mfma_f32_16x16x32_bf16 v[24:27], v[136:139], v[204:207], v[24:27]
	v_mfma_f32_16x16x32_bf16 v[12:15], v[128:131], v[212:215], v[12:15]
	v_mfma_f32_16x16x32_bf16 v[8:11], v[136:139], v[212:215], v[8:11]
	v_mfma_f32_16x16x32_bf16 v[60:63], v[132:135], v[180:183], v[60:63]
	v_mfma_f32_16x16x32_bf16 v[56:59], v[140:143], v[180:183], v[56:59]
	v_mfma_f32_16x16x32_bf16 v[44:47], v[132:135], v[198:201], v[44:47]
	v_mfma_f32_16x16x32_bf16 v[40:43], v[140:143], v[198:201], v[40:43]
	v_mfma_f32_16x16x32_bf16 v[28:31], v[132:135], v[208:211], v[28:31]
	v_mfma_f32_16x16x32_bf16 v[24:27], v[140:143], v[208:211], v[24:27]
	v_mfma_f32_16x16x32_bf16 v[12:15], v[132:135], v[216:219], v[12:15]
	v_mfma_f32_16x16x32_bf16 v[8:11], v[140:143], v[216:219], v[8:11]
	s_setprio 0
	s_setprio 1
	v_mfma_f32_16x16x32_bf16 v[52:55], v[144:147], v[176:179], v[52:55]
	v_mfma_f32_16x16x32_bf16 v[48:51], v[168:171], v[176:179], v[48:51]
	v_mfma_f32_16x16x32_bf16 v[36:39], v[144:147], v[192:195], v[36:39]
	v_mfma_f32_16x16x32_bf16 v[32:35], v[168:171], v[192:195], v[32:35]
	v_mfma_f32_16x16x32_bf16 v[20:23], v[144:147], v[204:207], v[20:23]
	v_mfma_f32_16x16x32_bf16 v[16:19], v[168:171], v[204:207], v[16:19]
	v_mfma_f32_16x16x32_bf16 v[4:7], v[144:147], v[212:215], v[4:7]
	v_mfma_f32_16x16x32_bf16 v[0:3], v[168:171], v[212:215], v[0:3]
	v_mfma_f32_16x16x32_bf16 v[52:55], v[148:151], v[180:183], v[52:55]
	v_mfma_f32_16x16x32_bf16 v[48:51], v[172:175], v[180:183], v[48:51]
	v_mfma_f32_16x16x32_bf16 v[36:39], v[148:151], v[198:201], v[36:39]
	v_mfma_f32_16x16x32_bf16 v[32:35], v[172:175], v[198:201], v[32:35]
	s_barrier
	v_mfma_f32_16x16x32_bf16 v[20:23], v[148:151], v[208:211], v[20:23]
	v_mfma_f32_16x16x32_bf16 v[16:19], v[172:175], v[208:211], v[16:19]
	v_mfma_f32_16x16x32_bf16 v[4:7], v[148:151], v[216:219], v[4:7]
	v_mfma_f32_16x16x32_bf16 v[0:3], v[172:175], v[216:219], v[0:3]
	s_setprio 0
	s_add_i32 s58, s58, 2
	s_add_u32 s22, s22, 0x100
	s_addc_u32 s23, s23, 0
	s_add_u32 s56, s56, 0x100
	s_addc_u32 s57, s57, 0
	s_cmp_gt_u32 s58, 13
	s_cbranch_scc0 .LBB0_966
	s_and_b64 vcc, exec, s[28:29]
	s_cbranch_vccz .LBB0_969
	s_barrier

.LBB0_1048:
	ds_read_b128 v[146:149], v169
	ds_read_b128 v[150:153], v169 offset:1024
	ds_read_b128 v[154:157], v169 offset:2048
	ds_read_b128 v[160:163], v169 offset:3072
	ds_read_b128 v[178:181], v171
	ds_read_b128 v[182:185], v171 offset:1024
	ds_read_b128 v[186:189], v171 offset:2048
	ds_read_b128 v[190:193], v171 offset:3072
	s_add_u32 s4, s10, 0xfffc0080
	s_addc_u32 s5, s11, -1
	s_cmp_eq_u32 s55, 12
	s_cselect_b32 s13, s9, s5
	s_cselect_b32 s12, s31, s4
	s_cselect_b32 s5, s29, s54
	s_cselect_b32 s4, s52, s53
	v_lshl_add_u64 v[194:195], s[10:11], 0, v[138:139]
	s_add_i32 m0, s41, 0xc000
	ds_read_b128 v[198:201], v173
	ds_read_b128 v[204:207], v173 offset:1024
	ds_read_b128 v[208:211], v173 offset:2048
	ds_read_b128 v[212:215], v173 offset:3072
	ds_read_b128 v[216:219], v173 offset:4096
	ds_read_b128 v[220:223], v173 offset:5120
	ds_read_b128 v[224:227], v173 offset:6144
	ds_read_b128 v[228:231], v173 offset:7168
	global_load_lds_dwordx4 v[194:195], off
	v_lshl_add_u64 v[194:195], s[10:11], 0, v[140:141]
	s_add_i32 m0, s41, 0xe000
	s_nop 0
	global_load_lds_dwordx4 v[194:195], off
	s_waitcnt vmcnt(8)
	s_waitcnt lgkmcnt(0)
	s_barrier
	s_setprio 1
	s_waitcnt lgkmcnt(0)
	v_mfma_f32_16x16x32_bf16 v[124:127], v[146:149], v[198:201], v[124:127]
	v_mfma_f32_16x16x32_bf16 v[116:119], v[154:157], v[198:201], v[116:119]
	v_mfma_f32_16x16x32_bf16 v[108:111], v[146:149], v[208:211], v[108:111]
	v_mfma_f32_16x16x32_bf16 v[100:103], v[154:157], v[208:211], v[100:103]
	v_mfma_f32_16x16x32_bf16 v[92:95], v[146:149], v[216:219], v[92:95]
	v_mfma_f32_16x16x32_bf16 v[84:87], v[154:157], v[216:219], v[84:87]
	v_mfma_f32_16x16x32_bf16 v[76:79], v[146:149], v[224:227], v[76:79]
	v_mfma_f32_16x16x32_bf16 v[68:71], v[154:157], v[224:227], v[68:71]
	v_mfma_f32_16x16x32_bf16 v[124:127], v[150:153], v[204:207], v[124:127]
	v_mfma_f32_16x16x32_bf16 v[116:119], v[160:163], v[204:207], v[116:119]
	v_mfma_f32_16x16x32_bf16 v[108:111], v[150:153], v[212:215], v[108:111]
	v_mfma_f32_16x16x32_bf16 v[100:103], v[160:163], v[212:215], v[100:103]
	v_mfma_f32_16x16x32_bf16 v[92:95], v[150:153], v[220:223], v[92:95]
	v_mfma_f32_16x16x32_bf16 v[84:87], v[160:163], v[220:223], v[84:87]
	v_mfma_f32_16x16x32_bf16 v[76:79], v[150:153], v[228:231], v[76:79]
	v_mfma_f32_16x16x32_bf16 v[68:71], v[160:163], v[228:231], v[68:71]
	s_setprio 0
	s_setprio 1
	v_mfma_f32_16x16x32_bf16 v[120:123], v[178:181], v[198:201], v[120:123]
	v_mfma_f32_16x16x32_bf16 v[112:115], v[186:189], v[198:201], v[112:115]
	v_mfma_f32_16x16x32_bf16 v[104:107], v[178:181], v[208:211], v[104:107]
	v_mfma_f32_16x16x32_bf16 v[96:99], v[186:189], v[208:211], v[96:99]
	v_mfma_f32_16x16x32_bf16 v[88:91], v[178:181], v[216:219], v[88:91]
	v_mfma_f32_16x16x32_bf16 v[80:83], v[186:189], v[216:219], v[80:83]
	v_mfma_f32_16x16x32_bf16 v[72:75], v[178:181], v[224:227], v[72:75]
	v_mfma_f32_16x16x32_bf16 v[64:67], v[186:189], v[224:227], v[64:67]
	v_mfma_f32_16x16x32_bf16 v[120:123], v[182:185], v[204:207], v[120:123]
	v_mfma_f32_16x16x32_bf16 v[112:115], v[190:193], v[204:207], v[112:115]
	v_mfma_f32_16x16x32_bf16 v[104:107], v[182:185], v[212:215], v[104:107]
	v_mfma_f32_16x16x32_bf16 v[96:99], v[190:193], v[212:215], v[96:99]
	s_barrier
	v_mfma_f32_16x16x32_bf16 v[88:91], v[182:185], v[220:223], v[88:91]
	v_mfma_f32_16x16x32_bf16 v[80:83], v[190:193], v[220:223], v[80:83]
	v_mfma_f32_16x16x32_bf16 v[72:75], v[182:185], v[228:231], v[72:75]
	v_mfma_f32_16x16x32_bf16 v[64:67], v[190:193], v[228:231], v[64:67]
	s_setprio 0
	s_add_i32 s56, s48, s39
	v_lshl_add_u64 v[194:195], s[4:5], 0, v[132:133]
	s_mov_b32 m0, s56
	ds_read_b128 v[198:201], v173 offset:16384
	ds_read_b128 v[204:207], v173 offset:17408
	ds_read_b128 v[208:211], v173 offset:18432
	ds_read_b128 v[212:215], v173 offset:19456
	ds_read_b128 v[216:219], v173 offset:20480
	ds_read_b128 v[220:223], v173 offset:21504
	ds_read_b128 v[224:227], v173 offset:22528
	ds_read_b128 v[228:231], v173 offset:23552
	global_load_lds_dwordx4 v[194:195], off
	s_add_i32 m0, s56, 0x2000
	s_add_u32 s56, s4, 0x40000
	v_lshl_add_u64 v[232:233], s[4:5], 0, v[128:129]
	s_addc_u32 s57, s5, 0
	s_add_i32 s58, s49, s39
	global_load_lds_dwordx4 v[232:233], off
	v_lshl_add_u64 v[234:235], s[56:57], 0, v[132:133]
	s_mov_b32 m0, s58
	v_lshl_add_u64 v[236:237], s[12:13], 0, v[130:131]
	global_load_lds_dwordx4 v[234:235], off
	v_lshl_add_u64 v[234:235], s[56:57], 0, v[128:129]
	s_add_i32 m0, s58, 0x2000
	s_nop 0
	global_load_lds_dwordx4 v[234:235], off
	v_lshl_add_u64 v[234:235], s[12:13], 0, v[134:135]
	s_mov_b32 m0, s41
	s_nop 0
	global_load_lds_dwordx4 v[234:235], off
	s_mov_b32 m0, s42
	s_nop 0
	global_load_lds_dwordx4 v[236:237], off
	s_waitcnt vmcnt(8)
	s_waitcnt lgkmcnt(0)
	s_barrier
	s_setprio 1
	s_waitcnt lgkmcnt(0)
	v_mfma_f32_16x16x32_bf16 v[60:63], v[146:149], v[198:201], v[60:63]
	v_mfma_f32_16x16x32_bf16 v[52:55], v[154:157], v[198:201], v[52:55]
	v_mfma_f32_16x16x32_bf16 v[44:47], v[146:149], v[208:211], v[44:47]
	v_mfma_f32_16x16x32_bf16 v[36:39], v[154:157], v[208:211], v[36:39]
	v_mfma_f32_16x16x32_bf16 v[28:31], v[146:149], v[216:219], v[28:31]
	v_mfma_f32_16x16x32_bf16 v[20:23], v[154:157], v[216:219], v[20:23]
	v_mfma_f32_16x16x32_bf16 v[12:15], v[146:149], v[224:227], v[12:15]
	v_mfma_f32_16x16x32_bf16 v[4:7], v[154:157], v[224:227], v[4:7]
	v_mfma_f32_16x16x32_bf16 v[60:63], v[150:153], v[204:207], v[60:63]
	v_mfma_f32_16x16x32_bf16 v[52:55], v[160:163], v[204:207], v[52:55]
	v_mfma_f32_16x16x32_bf16 v[44:47], v[150:153], v[212:215], v[44:47]
	v_mfma_f32_16x16x32_bf16 v[36:39], v[160:163], v[212:215], v[36:39]
	v_mfma_f32_16x16x32_bf16 v[28:31], v[150:153], v[220:223], v[28:31]
	v_mfma_f32_16x16x32_bf16 v[20:23], v[160:163], v[220:223], v[20:23]
	v_mfma_f32_16x16x32_bf16 v[12:15], v[150:153], v[228:231], v[12:15]
	v_mfma_f32_16x16x32_bf16 v[4:7], v[160:163], v[228:231], v[4:7]
	s_setprio 0
	s_setprio 1
	v_mfma_f32_16x16x32_bf16 v[56:59], v[178:181], v[198:201], v[56:59]
	v_mfma_f32_16x16x32_bf16 v[48:51], v[186:189], v[198:201], v[48:51]
	v_mfma_f32_16x16x32_bf16 v[40:43], v[178:181], v[208:211], v[40:43]
	v_mfma_f32_16x16x32_bf16 v[32:35], v[186:189], v[208:211], v[32:35]
	v_mfma_f32_16x16x32_bf16 v[24:27], v[178:181], v[216:219], v[24:27]
	v_mfma_f32_16x16x32_bf16 v[16:19], v[186:189], v[216:219], v[16:19]
	v_mfma_f32_16x16x32_bf16 v[8:11], v[178:181], v[224:227], v[8:11]
	v_mfma_f32_16x16x32_bf16 v[0:3], v[186:189], v[224:227], v[0:3]
	v_mfma_f32_16x16x32_bf16 v[56:59], v[182:185], v[204:207], v[56:59]
	v_mfma_f32_16x16x32_bf16 v[48:51], v[190:193], v[204:207], v[48:51]
	v_mfma_f32_16x16x32_bf16 v[40:43], v[182:185], v[212:215], v[40:43]
	v_mfma_f32_16x16x32_bf16 v[32:35], v[190:193], v[212:215], v[32:35]
	s_barrier
	v_mfma_f32_16x16x32_bf16 v[24:27], v[182:185], v[220:223], v[24:27]
	v_mfma_f32_16x16x32_bf16 v[16:19], v[190:193], v[220:223], v[16:19]
	v_mfma_f32_16x16x32_bf16 v[8:11], v[182:185], v[228:231], v[8:11]
	v_mfma_f32_16x16x32_bf16 v[0:3], v[190:193], v[228:231], v[0:3]
	s_setprio 0
	s_add_i32 s56, 0, 0x18000
	v_add_u32_e32 v158, s56, v165
	s_add_i32 s57, 0, 0x1c000
	ds_read_b128 v[146:149], v158
	ds_read_b128 v[150:153], v158 offset:1024
	ds_read_b128 v[154:157], v158 offset:2048
	ds_read_b128 v[160:163], v158 offset:3072
	v_add_u32_e32 v158, s57, v165
	ds_read_b128 v[178:181], v158
	ds_read_b128 v[182:185], v158 offset:1024
	ds_read_b128 v[186:189], v158 offset:2048
	ds_read_b128 v[190:193], v158 offset:3072
	s_add_u32 s12, s12, 0x40000
	s_addc_u32 s13, s13, 0
	s_mov_b32 m0, s43
	v_lshl_add_u64 v[238:239], s[12:13], 0, v[134:135]
	ds_read_b128 v[198:201], v173 offset:32768
	ds_read_b128 v[204:207], v173 offset:33792
	ds_read_b128 v[208:211], v173 offset:34816
	ds_read_b128 v[212:215], v173 offset:35840
	ds_read_b128 v[216:219], v173 offset:36864
	ds_read_b128 v[220:223], v173 offset:37888
	ds_read_b128 v[224:227], v173 offset:38912
	ds_read_b128 v[228:231], v173 offset:39936
	global_load_lds_dwordx4 v[238:239], off
	v_lshl_add_u64 v[238:239], s[12:13], 0, v[130:131]
	s_mov_b32 m0, s44
	s_nop 0
	global_load_lds_dwordx4 v[238:239], off
	s_waitcnt vmcnt(8)
	s_waitcnt lgkmcnt(0)
	s_barrier
	s_setprio 1
	s_waitcnt lgkmcnt(0)
	v_mfma_f32_16x16x32_bf16 v[124:127], v[146:149], v[198:201], v[124:127]
	v_mfma_f32_16x16x32_bf16 v[116:119], v[154:157], v[198:201], v[116:119]
	v_mfma_f32_16x16x32_bf16 v[108:111], v[146:149], v[208:211], v[108:111]
	v_mfma_f32_16x16x32_bf16 v[100:103], v[154:157], v[208:211], v[100:103]
	v_mfma_f32_16x16x32_bf16 v[92:95], v[146:149], v[216:219], v[92:95]
	v_mfma_f32_16x16x32_bf16 v[84:87], v[154:157], v[216:219], v[84:87]
	v_mfma_f32_16x16x32_bf16 v[76:79], v[146:149], v[224:227], v[76:79]
	v_mfma_f32_16x16x32_bf16 v[68:71], v[154:157], v[224:227], v[68:71]
	v_mfma_f32_16x16x32_bf16 v[124:127], v[150:153], v[204:207], v[124:127]
	v_mfma_f32_16x16x32_bf16 v[116:119], v[160:163], v[204:207], v[116:119]
	v_mfma_f32_16x16x32_bf16 v[108:111], v[150:153], v[212:215], v[108:111]
	v_mfma_f32_16x16x32_bf16 v[100:103], v[160:163], v[212:215], v[100:103]
	v_mfma_f32_16x16x32_bf16 v[92:95], v[150:153], v[220:223], v[92:95]
	v_mfma_f32_16x16x32_bf16 v[84:87], v[160:163], v[220:223], v[84:87]
	v_mfma_f32_16x16x32_bf16 v[76:79], v[150:153], v[228:231], v[76:79]
	v_mfma_f32_16x16x32_bf16 v[68:71], v[160:163], v[228:231], v[68:71]
	s_setprio 0
	s_setprio 1
	v_mfma_f32_16x16x32_bf16 v[120:123], v[178:181], v[198:201], v[120:123]
	v_mfma_f32_16x16x32_bf16 v[112:115], v[186:189], v[198:201], v[112:115]
	v_mfma_f32_16x16x32_bf16 v[104:107], v[178:181], v[208:211], v[104:107]
	v_mfma_f32_16x16x32_bf16 v[96:99], v[186:189], v[208:211], v[96:99]
	v_mfma_f32_16x16x32_bf16 v[88:91], v[178:181], v[216:219], v[88:91]
	v_mfma_f32_16x16x32_bf16 v[80:83], v[186:189], v[216:219], v[80:83]
	v_mfma_f32_16x16x32_bf16 v[72:75], v[178:181], v[224:227], v[72:75]
	v_mfma_f32_16x16x32_bf16 v[64:67], v[186:189], v[224:227], v[64:67]
	v_mfma_f32_16x16x32_bf16 v[120:123], v[182:185], v[204:207], v[120:123]
	v_mfma_f32_16x16x32_bf16 v[112:115], v[190:193], v[204:207], v[112:115]
	v_mfma_f32_16x16x32_bf16 v[104:107], v[182:185], v[212:215], v[104:107]
	v_mfma_f32_16x16x32_bf16 v[96:99], v[190:193], v[212:215], v[96:99]
	s_barrier
	v_mfma_f32_16x16x32_bf16 v[88:91], v[182:185], v[220:223], v[88:91]
	v_mfma_f32_16x16x32_bf16 v[80:83], v[190:193], v[220:223], v[80:83]
	v_mfma_f32_16x16x32_bf16 v[72:75], v[182:185], v[228:231], v[72:75]
	v_mfma_f32_16x16x32_bf16 v[64:67], v[190:193], v[228:231], v[64:67]
	s_setprio 0
	s_add_i32 s12, s56, s39
	v_lshl_add_u64 v[194:195], v[194:195], 0, s[24:25]
	s_mov_b32 m0, s12
	ds_read_b128 v[198:201], v173 offset:49152
	ds_read_b128 v[204:207], v173 offset:50176
	ds_read_b128 v[208:211], v173 offset:51200
	ds_read_b128 v[212:215], v173 offset:52224
	ds_read_b128 v[216:219], v173 offset:53248
	ds_read_b128 v[220:223], v173 offset:54272
	ds_read_b128 v[224:227], v173 offset:55296
	ds_read_b128 v[228:231], v173 offset:56320
	global_load_lds_dwordx4 v[194:195], off
	s_add_i32 m0, s12, 0x2000
	s_add_u32 s4, s4, 0x40080
	v_lshl_add_u64 v[194:195], v[232:233], 0, s[24:25]
	s_addc_u32 s5, s5, 0
	s_add_i32 s12, s57, s39
	global_load_lds_dwordx4 v[194:195], off
	v_lshl_add_u64 v[194:195], s[4:5], 0, v[132:133]
	s_mov_b32 m0, s12
	s_nop 0
	global_load_lds_dwordx4 v[194:195], off
	v_lshl_add_u64 v[194:195], s[4:5], 0, v[128:129]
	s_add_i32 m0, s12, 0x2000
	s_nop 0
	global_load_lds_dwordx4 v[194:195], off
	v_lshl_add_u64 v[194:195], v[234:235], 0, s[24:25]
	s_mov_b32 m0, s46
	s_nop 0
	global_load_lds_dwordx4 v[194:195], off
	v_lshl_add_u64 v[194:195], v[236:237], 0, s[24:25]
	s_mov_b32 m0, s47
	s_nop 0
	global_load_lds_dwordx4 v[194:195], off
	s_waitcnt vmcnt(8)
	s_waitcnt lgkmcnt(0)
	s_barrier
	s_setprio 1
	s_waitcnt lgkmcnt(0)
	v_mfma_f32_16x16x32_bf16 v[60:63], v[146:149], v[198:201], v[60:63]
	v_mfma_f32_16x16x32_bf16 v[52:55], v[154:157], v[198:201], v[52:55]
	v_mfma_f32_16x16x32_bf16 v[44:47], v[146:149], v[208:211], v[44:47]
	v_mfma_f32_16x16x32_bf16 v[36:39], v[154:157], v[208:211], v[36:39]
	v_mfma_f32_16x16x32_bf16 v[28:31], v[146:149], v[216:219], v[28:31]
	v_mfma_f32_16x16x32_bf16 v[20:23], v[154:157], v[216:219], v[20:23]
	v_mfma_f32_16x16x32_bf16 v[12:15], v[146:149], v[224:227], v[12:15]
	v_mfma_f32_16x16x32_bf16 v[4:7], v[154:157], v[224:227], v[4:7]
	v_mfma_f32_16x16x32_bf16 v[60:63], v[150:153], v[204:207], v[60:63]
	v_mfma_f32_16x16x32_bf16 v[52:55], v[160:163], v[204:207], v[52:55]
	v_mfma_f32_16x16x32_bf16 v[44:47], v[150:153], v[212:215], v[44:47]
	v_mfma_f32_16x16x32_bf16 v[36:39], v[160:163], v[212:215], v[36:39]
	v_mfma_f32_16x16x32_bf16 v[28:31], v[150:153], v[220:223], v[28:31]
	v_mfma_f32_16x16x32_bf16 v[20:23], v[160:163], v[220:223], v[20:23]
	v_mfma_f32_16x16x32_bf16 v[12:15], v[150:153], v[228:231], v[12:15]
	v_mfma_f32_16x16x32_bf16 v[4:7], v[160:163], v[228:231], v[4:7]
	s_setprio 0
	s_setprio 1
	v_mfma_f32_16x16x32_bf16 v[56:59], v[178:181], v[198:201], v[56:59]
	v_mfma_f32_16x16x32_bf16 v[48:51], v[186:189], v[198:201], v[48:51]
	v_mfma_f32_16x16x32_bf16 v[40:43], v[178:181], v[208:211], v[40:43]
	v_mfma_f32_16x16x32_bf16 v[32:35], v[186:189], v[208:211], v[32:35]
	v_mfma_f32_16x16x32_bf16 v[24:27], v[178:181], v[216:219], v[24:27]
	v_mfma_f32_16x16x32_bf16 v[16:19], v[186:189], v[216:219], v[16:19]
	v_mfma_f32_16x16x32_bf16 v[8:11], v[178:181], v[224:227], v[8:11]
	v_mfma_f32_16x16x32_bf16 v[0:3], v[186:189], v[224:227], v[0:3]
	v_mfma_f32_16x16x32_bf16 v[56:59], v[182:185], v[204:207], v[56:59]
	v_mfma_f32_16x16x32_bf16 v[48:51], v[190:193], v[204:207], v[48:51]
	v_mfma_f32_16x16x32_bf16 v[40:43], v[182:185], v[212:215], v[40:43]
	v_mfma_f32_16x16x32_bf16 v[32:35], v[190:193], v[212:215], v[32:35]
	s_barrier
	v_mfma_f32_16x16x32_bf16 v[24:27], v[182:185], v[220:223], v[24:27]
	v_mfma_f32_16x16x32_bf16 v[16:19], v[190:193], v[220:223], v[16:19]
	v_mfma_f32_16x16x32_bf16 v[8:11], v[182:185], v[228:231], v[8:11]
	v_mfma_f32_16x16x32_bf16 v[0:3], v[190:193], v[228:231], v[0:3]
	s_setprio 0
	s_add_i32 s55, s55, 2
	s_add_u32 s10, s10, 0x100
	s_addc_u32 s11, s11, 0
	s_add_u32 s53, s53, 0x100
	s_addc_u32 s54, s54, 0
	s_cmp_gt_u32 s55, 13
	s_cbranch_scc0 .LBB0_1048
	s_and_b64 vcc, exec, s[26:27]
	s_cbranch_vccz .LBB0_1051
	s_barrier

.LBB0_1124:
	ds_read_b128 v[128:131], v189
	ds_read_b128 v[132:135], v189 offset:1024
	ds_read_b128 v[136:139], v189 offset:2048
	ds_read_b128 v[140:143], v189 offset:3072
	ds_read_b128 v[144:147], v190
	ds_read_b128 v[148:151], v190 offset:1024
	ds_read_b128 v[168:171], v190 offset:2048
	ds_read_b128 v[172:175], v190 offset:3072
	s_add_u32 s34, s30, 0x100
	s_addc_u32 s35, s31, 0
	s_cmp_eq_u32 s56, 40
	s_cselect_b32 s39, s9, s35
	s_cselect_b32 s38, s8, s34
	s_cselect_b32 s37, s29, s55
	s_cselect_b32 s36, s28, s54
	v_lshl_add_u64 v[184:185], s[30:31], 0, v[160:161]
	s_add_i32 m0, s42, 0xc000
	ds_read_b128 v[176:179], v191
	ds_read_b128 v[180:183], v191 offset:1024
	ds_read_b128 v[192:195], v191 offset:2048
	ds_read_b128 v[198:201], v191 offset:3072
	ds_read_b128 v[204:207], v191 offset:4096
	ds_read_b128 v[208:211], v191 offset:5120
	ds_read_b128 v[212:215], v191 offset:6144
	ds_read_b128 v[216:219], v191 offset:7168
	global_load_lds_dwordx4 v[184:185], off
	v_lshl_add_u64 v[184:185], s[30:31], 0, v[162:163]
	s_add_i32 m0, s42, 0xe000
	s_nop 0
	global_load_lds_dwordx4 v[184:185], off
	s_waitcnt vmcnt(8)
	s_waitcnt lgkmcnt(0)
	s_barrier
	s_setprio 1
	s_waitcnt lgkmcnt(0)
	v_mfma_f32_16x16x32_bf16 v[124:127], v[128:131], v[176:179], v[124:127]
	v_mfma_f32_16x16x32_bf16 v[120:123], v[136:139], v[176:179], v[120:123]
	v_mfma_f32_16x16x32_bf16 v[108:111], v[128:131], v[192:195], v[108:111]
	v_mfma_f32_16x16x32_bf16 v[104:107], v[136:139], v[192:195], v[104:107]
	v_mfma_f32_16x16x32_bf16 v[92:95], v[128:131], v[204:207], v[92:95]
	v_mfma_f32_16x16x32_bf16 v[88:91], v[136:139], v[204:207], v[88:91]
	v_mfma_f32_16x16x32_bf16 v[76:79], v[128:131], v[212:215], v[76:79]
	v_mfma_f32_16x16x32_bf16 v[72:75], v[136:139], v[212:215], v[72:75]
	v_mfma_f32_16x16x32_bf16 v[124:127], v[132:135], v[180:183], v[124:127]
	v_mfma_f32_16x16x32_bf16 v[120:123], v[140:143], v[180:183], v[120:123]
	v_mfma_f32_16x16x32_bf16 v[108:111], v[132:135], v[198:201], v[108:111]
	v_mfma_f32_16x16x32_bf16 v[104:107], v[140:143], v[198:201], v[104:107]
	v_mfma_f32_16x16x32_bf16 v[92:95], v[132:135], v[208:211], v[92:95]
	v_mfma_f32_16x16x32_bf16 v[88:91], v[140:143], v[208:211], v[88:91]
	v_mfma_f32_16x16x32_bf16 v[76:79], v[132:135], v[216:219], v[76:79]
	v_mfma_f32_16x16x32_bf16 v[72:75], v[140:143], v[216:219], v[72:75]
	s_setprio 0
	s_setprio 1
	v_mfma_f32_16x16x32_bf16 v[116:119], v[144:147], v[176:179], v[116:119]
	v_mfma_f32_16x16x32_bf16 v[112:115], v[168:171], v[176:179], v[112:115]
	v_mfma_f32_16x16x32_bf16 v[100:103], v[144:147], v[192:195], v[100:103]
	v_mfma_f32_16x16x32_bf16 v[96:99], v[168:171], v[192:195], v[96:99]
	v_mfma_f32_16x16x32_bf16 v[84:87], v[144:147], v[204:207], v[84:87]
	v_mfma_f32_16x16x32_bf16 v[80:83], v[168:171], v[204:207], v[80:83]
	v_mfma_f32_16x16x32_bf16 v[68:71], v[144:147], v[212:215], v[68:71]
	v_mfma_f32_16x16x32_bf16 v[64:67], v[168:171], v[212:215], v[64:67]
	v_mfma_f32_16x16x32_bf16 v[116:119], v[148:151], v[180:183], v[116:119]
	v_mfma_f32_16x16x32_bf16 v[112:115], v[172:175], v[180:183], v[112:115]
	v_mfma_f32_16x16x32_bf16 v[100:103], v[148:151], v[198:201], v[100:103]
	v_mfma_f32_16x16x32_bf16 v[96:99], v[172:175], v[198:201], v[96:99]
	s_barrier
	v_mfma_f32_16x16x32_bf16 v[84:87], v[148:151], v[208:211], v[84:87]
	v_mfma_f32_16x16x32_bf16 v[80:83], v[172:175], v[208:211], v[80:83]
	v_mfma_f32_16x16x32_bf16 v[68:71], v[148:151], v[216:219], v[68:71]
	v_mfma_f32_16x16x32_bf16 v[64:67], v[172:175], v[216:219], v[64:67]
	s_setprio 0
	s_add_i32 s30, s48, s41
	v_lshl_add_u64 v[184:185], s[36:37], 0, v[154:155]
	s_mov_b32 m0, s30
	ds_read_b128 v[176:179], v191 offset:16384
	ds_read_b128 v[180:183], v191 offset:17408
	ds_read_b128 v[192:195], v191 offset:18432
	ds_read_b128 v[198:201], v191 offset:19456
	ds_read_b128 v[204:207], v191 offset:20480
	ds_read_b128 v[208:211], v191 offset:21504
	ds_read_b128 v[212:215], v191 offset:22528
	ds_read_b128 v[216:219], v191 offset:23552
	global_load_lds_dwordx4 v[184:185], off
	s_add_i32 m0, s30, 0x2000
	s_add_u32 s30, s36, 0xb0000
	v_lshl_add_u64 v[220:221], s[36:37], 0, v[158:159]
	s_addc_u32 s31, s37, 0
	s_add_i32 s57, s49, s41
	global_load_lds_dwordx4 v[220:221], off
	v_lshl_add_u64 v[222:223], s[30:31], 0, v[154:155]
	s_mov_b32 m0, s57
	v_lshl_add_u64 v[224:225], s[38:39], 0, v[156:157]
	global_load_lds_dwordx4 v[222:223], off
	v_lshl_add_u64 v[222:223], s[30:31], 0, v[158:159]
	s_add_i32 m0, s57, 0x2000
	s_nop 0
	global_load_lds_dwordx4 v[222:223], off
	v_lshl_add_u64 v[222:223], s[38:39], 0, v[152:153]
	s_mov_b32 m0, s42
	s_nop 0
	global_load_lds_dwordx4 v[222:223], off
	s_mov_b32 m0, s33
	s_nop 0
	global_load_lds_dwordx4 v[224:225], off
	s_waitcnt vmcnt(8)
	s_waitcnt lgkmcnt(0)
	s_barrier
	s_setprio 1
	s_waitcnt lgkmcnt(0)
	v_mfma_f32_16x16x32_bf16 v[60:63], v[128:131], v[176:179], v[60:63]
	v_mfma_f32_16x16x32_bf16 v[56:59], v[136:139], v[176:179], v[56:59]
	v_mfma_f32_16x16x32_bf16 v[44:47], v[128:131], v[192:195], v[44:47]
	v_mfma_f32_16x16x32_bf16 v[40:43], v[136:139], v[192:195], v[40:43]
	v_mfma_f32_16x16x32_bf16 v[28:31], v[128:131], v[204:207], v[28:31]
	v_mfma_f32_16x16x32_bf16 v[24:27], v[136:139], v[204:207], v[24:27]
	v_mfma_f32_16x16x32_bf16 v[12:15], v[128:131], v[212:215], v[12:15]
	v_mfma_f32_16x16x32_bf16 v[8:11], v[136:139], v[212:215], v[8:11]
	v_mfma_f32_16x16x32_bf16 v[60:63], v[132:135], v[180:183], v[60:63]
	v_mfma_f32_16x16x32_bf16 v[56:59], v[140:143], v[180:183], v[56:59]
	v_mfma_f32_16x16x32_bf16 v[44:47], v[132:135], v[198:201], v[44:47]
	v_mfma_f32_16x16x32_bf16 v[40:43], v[140:143], v[198:201], v[40:43]
	v_mfma_f32_16x16x32_bf16 v[28:31], v[132:135], v[208:211], v[28:31]
	v_mfma_f32_16x16x32_bf16 v[24:27], v[140:143], v[208:211], v[24:27]
	v_mfma_f32_16x16x32_bf16 v[12:15], v[132:135], v[216:219], v[12:15]
	v_mfma_f32_16x16x32_bf16 v[8:11], v[140:143], v[216:219], v[8:11]
	s_setprio 0
	s_setprio 1
	v_mfma_f32_16x16x32_bf16 v[52:55], v[144:147], v[176:179], v[52:55]
	v_mfma_f32_16x16x32_bf16 v[48:51], v[168:171], v[176:179], v[48:51]
	v_mfma_f32_16x16x32_bf16 v[36:39], v[144:147], v[192:195], v[36:39]
	v_mfma_f32_16x16x32_bf16 v[32:35], v[168:171], v[192:195], v[32:35]
	v_mfma_f32_16x16x32_bf16 v[20:23], v[144:147], v[204:207], v[20:23]
	v_mfma_f32_16x16x32_bf16 v[16:19], v[168:171], v[204:207], v[16:19]
	v_mfma_f32_16x16x32_bf16 v[4:7], v[144:147], v[212:215], v[4:7]
	v_mfma_f32_16x16x32_bf16 v[0:3], v[168:171], v[212:215], v[0:3]
	v_mfma_f32_16x16x32_bf16 v[52:55], v[148:151], v[180:183], v[52:55]
	v_mfma_f32_16x16x32_bf16 v[48:51], v[172:175], v[180:183], v[48:51]
	v_mfma_f32_16x16x32_bf16 v[36:39], v[148:151], v[198:201], v[36:39]
	v_mfma_f32_16x16x32_bf16 v[32:35], v[172:175], v[198:201], v[32:35]
	s_barrier
	v_mfma_f32_16x16x32_bf16 v[20:23], v[148:151], v[208:211], v[20:23]
	v_mfma_f32_16x16x32_bf16 v[16:19], v[172:175], v[208:211], v[16:19]
	v_mfma_f32_16x16x32_bf16 v[4:7], v[148:151], v[216:219], v[4:7]
	v_mfma_f32_16x16x32_bf16 v[0:3], v[172:175], v[216:219], v[0:3]
	s_setprio 0
	s_add_i32 s57, 0, 0x18000
	s_add_i32 s58, 0, 0x1c000
	v_add_u32_e32 v140, s57, v187
	v_add_u32_e32 v172, s58, v187
	ds_read_b128 v[128:131], v140
	ds_read_b128 v[132:135], v140 offset:1024
	ds_read_b128 v[136:139], v140 offset:2048
	ds_read_b128 v[140:143], v140 offset:3072
	ds_read_b128 v[144:147], v172
	ds_read_b128 v[148:151], v172 offset:1024
	ds_read_b128 v[168:171], v172 offset:2048
	ds_read_b128 v[172:175], v172 offset:3072
	s_add_u32 s30, s38, 0xb0000
	s_addc_u32 s31, s39, 0
	s_mov_b32 m0, s43
	v_lshl_add_u64 v[226:227], s[30:31], 0, v[152:153]
	ds_read_b128 v[176:179], v191 offset:32768
	ds_read_b128 v[180:183], v191 offset:33792
	ds_read_b128 v[192:195], v191 offset:34816
	ds_read_b128 v[198:201], v191 offset:35840
	ds_read_b128 v[204:207], v191 offset:36864
	ds_read_b128 v[208:211], v191 offset:37888
	ds_read_b128 v[212:215], v191 offset:38912
	ds_read_b128 v[216:219], v191 offset:39936
	global_load_lds_dwordx4 v[226:227], off
	v_lshl_add_u64 v[226:227], s[30:31], 0, v[156:157]
	s_mov_b32 m0, s44
	s_nop 0
	global_load_lds_dwordx4 v[226:227], off
	s_waitcnt vmcnt(8)
	s_waitcnt lgkmcnt(0)
	s_barrier
	s_setprio 1
	s_waitcnt lgkmcnt(0)
	v_mfma_f32_16x16x32_bf16 v[124:127], v[128:131], v[176:179], v[124:127]
	v_mfma_f32_16x16x32_bf16 v[120:123], v[136:139], v[176:179], v[120:123]
	v_mfma_f32_16x16x32_bf16 v[108:111], v[128:131], v[192:195], v[108:111]
	v_mfma_f32_16x16x32_bf16 v[104:107], v[136:139], v[192:195], v[104:107]
	v_mfma_f32_16x16x32_bf16 v[92:95], v[128:131], v[204:207], v[92:95]
	v_mfma_f32_16x16x32_bf16 v[88:91], v[136:139], v[204:207], v[88:91]
	v_mfma_f32_16x16x32_bf16 v[76:79], v[128:131], v[212:215], v[76:79]
	v_mfma_f32_16x16x32_bf16 v[72:75], v[136:139], v[212:215], v[72:75]
	v_mfma_f32_16x16x32_bf16 v[124:127], v[132:135], v[180:183], v[124:127]
	v_mfma_f32_16x16x32_bf16 v[120:123], v[140:143], v[180:183], v[120:123]
	v_mfma_f32_16x16x32_bf16 v[108:111], v[132:135], v[198:201], v[108:111]
	v_mfma_f32_16x16x32_bf16 v[104:107], v[140:143], v[198:201], v[104:107]
	v_mfma_f32_16x16x32_bf16 v[92:95], v[132:135], v[208:211], v[92:95]
	v_mfma_f32_16x16x32_bf16 v[88:91], v[140:143], v[208:211], v[88:91]
	v_mfma_f32_16x16x32_bf16 v[76:79], v[132:135], v[216:219], v[76:79]
	v_mfma_f32_16x16x32_bf16 v[72:75], v[140:143], v[216:219], v[72:75]
	s_setprio 0
	s_setprio 1
	v_mfma_f32_16x16x32_bf16 v[116:119], v[144:147], v[176:179], v[116:119]
	v_mfma_f32_16x16x32_bf16 v[112:115], v[168:171], v[176:179], v[112:115]
	v_mfma_f32_16x16x32_bf16 v[100:103], v[144:147], v[192:195], v[100:103]
	v_mfma_f32_16x16x32_bf16 v[96:99], v[168:171], v[192:195], v[96:99]
	v_mfma_f32_16x16x32_bf16 v[84:87], v[144:147], v[204:207], v[84:87]
	v_mfma_f32_16x16x32_bf16 v[80:83], v[168:171], v[204:207], v[80:83]
	v_mfma_f32_16x16x32_bf16 v[68:71], v[144:147], v[212:215], v[68:71]
	v_mfma_f32_16x16x32_bf16 v[64:67], v[168:171], v[212:215], v[64:67]
	v_mfma_f32_16x16x32_bf16 v[116:119], v[148:151], v[180:183], v[116:119]
	v_mfma_f32_16x16x32_bf16 v[112:115], v[172:175], v[180:183], v[112:115]
	v_mfma_f32_16x16x32_bf16 v[100:103], v[148:151], v[198:201], v[100:103]
	v_mfma_f32_16x16x32_bf16 v[96:99], v[172:175], v[198:201], v[96:99]
	s_barrier
	v_mfma_f32_16x16x32_bf16 v[84:87], v[148:151], v[208:211], v[84:87]
	v_mfma_f32_16x16x32_bf16 v[80:83], v[172:175], v[208:211], v[80:83]
	v_mfma_f32_16x16x32_bf16 v[68:71], v[148:151], v[216:219], v[68:71]
	v_mfma_f32_16x16x32_bf16 v[64:67], v[172:175], v[216:219], v[64:67]
	s_setprio 0
	s_add_i32 s30, s57, s41
	v_lshl_add_u64 v[184:185], v[184:185], 0, s[24:25]
	s_mov_b32 m0, s30
	ds_read_b128 v[176:179], v191 offset:49152
	ds_read_b128 v[180:183], v191 offset:50176
	ds_read_b128 v[192:195], v191 offset:51200
	ds_read_b128 v[198:201], v191 offset:52224
	ds_read_b128 v[204:207], v191 offset:53248
	ds_read_b128 v[208:211], v191 offset:54272
	ds_read_b128 v[212:215], v191 offset:55296
	ds_read_b128 v[216:219], v191 offset:56320
	global_load_lds_dwordx4 v[184:185], off
	s_add_i32 m0, s30, 0x2000
	s_add_u32 s30, s36, 0xb0080
	v_lshl_add_u64 v[184:185], v[220:221], 0, s[24:25]
	s_addc_u32 s31, s37, 0
	s_add_i32 s36, s58, s41
	global_load_lds_dwordx4 v[184:185], off
	v_lshl_add_u64 v[184:185], s[30:31], 0, v[154:155]
	s_mov_b32 m0, s36
	s_nop 0
	global_load_lds_dwordx4 v[184:185], off
	v_lshl_add_u64 v[184:185], s[30:31], 0, v[158:159]
	s_add_i32 m0, s36, 0x2000
	s_nop 0
	global_load_lds_dwordx4 v[184:185], off
	v_lshl_add_u64 v[184:185], v[222:223], 0, s[24:25]
	s_mov_b32 m0, s46
	s_nop 0
	global_load_lds_dwordx4 v[184:185], off
	v_lshl_add_u64 v[184:185], v[224:225], 0, s[24:25]
	s_mov_b32 m0, s47
	s_nop 0
	global_load_lds_dwordx4 v[184:185], off
	s_waitcnt vmcnt(8)
	s_waitcnt lgkmcnt(0)
	s_barrier
	s_setprio 1
	s_waitcnt lgkmcnt(0)
	v_mfma_f32_16x16x32_bf16 v[60:63], v[128:131], v[176:179], v[60:63]
	v_mfma_f32_16x16x32_bf16 v[56:59], v[136:139], v[176:179], v[56:59]
	v_mfma_f32_16x16x32_bf16 v[44:47], v[128:131], v[192:195], v[44:47]
	v_mfma_f32_16x16x32_bf16 v[40:43], v[136:139], v[192:195], v[40:43]
	v_mfma_f32_16x16x32_bf16 v[28:31], v[128:131], v[204:207], v[28:31]
	v_mfma_f32_16x16x32_bf16 v[24:27], v[136:139], v[204:207], v[24:27]
	v_mfma_f32_16x16x32_bf16 v[12:15], v[128:131], v[212:215], v[12:15]
	v_mfma_f32_16x16x32_bf16 v[8:11], v[136:139], v[212:215], v[8:11]
	v_mfma_f32_16x16x32_bf16 v[60:63], v[132:135], v[180:183], v[60:63]
	v_mfma_f32_16x16x32_bf16 v[56:59], v[140:143], v[180:183], v[56:59]
	v_mfma_f32_16x16x32_bf16 v[44:47], v[132:135], v[198:201], v[44:47]
	v_mfma_f32_16x16x32_bf16 v[40:43], v[140:143], v[198:201], v[40:43]
	v_mfma_f32_16x16x32_bf16 v[28:31], v[132:135], v[208:211], v[28:31]
	v_mfma_f32_16x16x32_bf16 v[24:27], v[140:143], v[208:211], v[24:27]
	v_mfma_f32_16x16x32_bf16 v[12:15], v[132:135], v[216:219], v[12:15]
	v_mfma_f32_16x16x32_bf16 v[8:11], v[140:143], v[216:219], v[8:11]
	s_setprio 0
	s_setprio 1
	v_mfma_f32_16x16x32_bf16 v[52:55], v[144:147], v[176:179], v[52:55]
	v_mfma_f32_16x16x32_bf16 v[48:51], v[168:171], v[176:179], v[48:51]
	v_mfma_f32_16x16x32_bf16 v[36:39], v[144:147], v[192:195], v[36:39]
	v_mfma_f32_16x16x32_bf16 v[32:35], v[168:171], v[192:195], v[32:35]
	v_mfma_f32_16x16x32_bf16 v[20:23], v[144:147], v[204:207], v[20:23]
	v_mfma_f32_16x16x32_bf16 v[16:19], v[168:171], v[204:207], v[16:19]
	v_mfma_f32_16x16x32_bf16 v[4:7], v[144:147], v[212:215], v[4:7]
	v_mfma_f32_16x16x32_bf16 v[0:3], v[168:171], v[212:215], v[0:3]
	v_mfma_f32_16x16x32_bf16 v[52:55], v[148:151], v[180:183], v[52:55]
	v_mfma_f32_16x16x32_bf16 v[48:51], v[172:175], v[180:183], v[48:51]
	v_mfma_f32_16x16x32_bf16 v[36:39], v[148:151], v[198:201], v[36:39]
	v_mfma_f32_16x16x32_bf16 v[32:35], v[172:175], v[198:201], v[32:35]
	s_barrier
	v_mfma_f32_16x16x32_bf16 v[20:23], v[148:151], v[208:211], v[20:23]
	v_mfma_f32_16x16x32_bf16 v[16:19], v[172:175], v[208:211], v[16:19]
	v_mfma_f32_16x16x32_bf16 v[4:7], v[148:151], v[216:219], v[4:7]
	v_mfma_f32_16x16x32_bf16 v[0:3], v[172:175], v[216:219], v[0:3]
	s_setprio 0
	s_add_i32 s56, s56, 2
	s_add_u32 s54, s54, 0x100
	s_addc_u32 s55, s55, 0
	s_cmp_gt_u32 s56, 41
	s_mov_b64 s[30:31], s[34:35]
	s_cbranch_scc0 .LBB0_1124
	s_and_b64 vcc, exec, s[26:27]
	s_cbranch_vccz .LBB0_1127
	s_barrier
